# LayerNorm / merge wave reductions by DPP + v_permlane32/16_swap butterflies instead of ds_bpermute round trips
# speedup vs baseline: 1.0050x; 1.0030x over previous
; __device__ __forceinline__ float bflo(unsigned u) { return __uint_as_float(u << 16); }
; __device__ __forceinline__ float bfhi(unsigned u) { return __uint_as_float(u & 0xffff0000u); }
; __device__ void ln_phase2(const bf16_t* __restrict__ mix, const float* __restrict__ Rf, const bf16_t* __restrict__ Rb, const float* __restrict__ gam, const float* __restrict__ bet, bf16_t* ob, float* of) {
;     ...
;     for (int row = blockIdx.x * 8 + wid; row < T_TOK; row += gridDim.x * 8) {
;         const size_t ro = (size_t)row * DM + lane * 8;
;         float v[32]; float s = 0.f;
; #pragma unroll
;         for (int j = 0; j < 4; ++j) {
;             const u32x4 m = *(const u32x4*)(mix + ro + 512 * j);
;             float r[8];
;             if (Rf) { const f32x4 a = *(const f32x4*)(Rf + ro + 512 * j), b = *(const f32x4*)(Rf + ro + 512 * j + 4);
;                 r[0] = a[0]; r[1] = a[1]; r[2] = a[2]; r[3] = a[3]; r[4] = b[0]; r[5] = b[1]; r[6] = b[2]; r[7] = b[3]; }
;             else { const u32x4 rb = *(const u32x4*)(Rb + ro + 512 * j);
;                 r[0] = bflo(rb.x); r[1] = bfhi(rb.x); r[2] = bflo(rb.y); r[3] = bfhi(rb.y); r[4] = bflo(rb.z); r[5] = bfhi(rb.z); r[6] = bflo(rb.w); r[7] = bfhi(rb.w); }
;             v[8 * j + 0] = DN_ALPHA * r[0] + bflo(m.x); v[8 * j + 1] = DN_ALPHA * r[1] + bfhi(m.x); v[8 * j + 2] = DN_ALPHA * r[2] + bflo(m.y); v[8 * j + 3] = DN_ALPHA * r[3] + bfhi(m.y);
;             v[8 * j + 4] = DN_ALPHA * r[4] + bflo(m.z); v[8 * j + 5] = DN_ALPHA * r[5] + bfhi(m.z); v[8 * j + 6] = DN_ALPHA * r[6] + bflo(m.w); v[8 * j + 7] = DN_ALPHA * r[7] + bfhi(m.w);
; #pragma unroll
;             for (int e = 0; e < 8; ++e) s += v[8 * j + e];
;         }
; #pragma unroll
;         for (int o = 32; o; o >>= 1) s += __shfl_xor(s, o);
;         const float mean = s * (1.0f / 2048.0f);
.LBB0_31:
	v_ashrrev_i32_e32 v1, 31, v0
	v_lshlrev_b64 v[88:89], 11, v[0:1]
	v_or_b32_e32 v88, v88, v84
	v_lshlrev_b64 v[68:69], 1, v[88:89]
	v_lshl_add_u64 v[70:71], s[68:69], 0, v[68:69]
	v_lshl_add_u64 v[72:73], s[92:93], 0, v[68:69]
	global_load_dwordx4 v[94:97], v[70:71], off
	global_load_dwordx4 v[98:101], v[72:73], off
	global_load_dwordx4 v[110:113], v[70:71], off offset:1024
	global_load_dwordx4 v[114:117], v[72:73], off offset:1024
	global_load_dwordx4 v[76:79], v[70:71], off offset:2048
	global_load_dwordx4 v[80:83], v[72:73], off offset:2048
	s_nop 0
	global_load_dwordx4 v[68:71], v[70:71], off offset:3072
	s_nop 0
	global_load_dwordx4 v[72:75], v[72:73], off offset:3072
	v_add_u32_e32 v0, s10, v0
	s_waitcnt vmcnt(0)
	v_lshlrev_b32_e32 v92, 16, v97
	v_and_b32_e32 v93, 0xffff0000, v97
	v_and_b32_e32 v97, 0xffff0000, v94
	s_waitcnt vmcnt(5)
	v_lshlrev_b32_e32 v102, 16, v110
	v_and_b32_e32 v103, 0xffff0000, v110
	v_lshlrev_b32_e32 v104, 16, v111
	s_waitcnt vmcnt(1)
	v_and_b32_e32 v90, 0xffff0000, v70
	s_waitcnt vmcnt(0)
	v_and_b32_e32 v86, 0xffff0000, v74
	v_lshlrev_b32_e32 v87, 16, v74
	v_lshlrev_b32_e32 v91, 16, v70
	v_and_b32_e32 v74, 0xffff0000, v75
	v_lshlrev_b32_e32 v75, 16, v75
	v_and_b32_e32 v70, 0xffff0000, v71
	v_lshlrev_b32_e32 v71, 16, v71
	v_pk_fma_f32 v[86:87], v[86:87], s[4:5], v[90:91] op_sel_hi:[1,0,1]
	v_pk_fma_f32 v[74:75], v[74:75], s[4:5], v[70:71] op_sel_hi:[1,0,1]
	v_lshl_add_u64 v[70:71], v[88:89], 2, s[90:91]
	v_lshlrev_b32_e32 v88, 16, v100
	v_and_b32_e32 v89, 0xffff0000, v100
	v_lshlrev_b32_e32 v90, 16, v96
	v_and_b32_e32 v91, 0xffff0000, v96
	v_pk_fma_f32 v[88:89], v[88:89], s[4:5], v[90:91] op_sel_hi:[1,0,1]
	v_lshlrev_b32_e32 v90, 16, v101
	v_and_b32_e32 v91, 0xffff0000, v101
	v_pk_fma_f32 v[90:91], v[90:91], s[4:5], v[92:93] op_sel_hi:[1,0,1]
	v_lshlrev_b32_e32 v92, 16, v98
	v_and_b32_e32 v93, 0xffff0000, v98
	v_lshlrev_b32_e32 v96, 16, v94
	v_pk_fma_f32 v[92:93], v[92:93], s[4:5], v[96:97] op_sel_hi:[1,0,1]
	v_lshlrev_b32_e32 v96, 16, v99
	v_add_f32_e32 v1, 0, v92
	v_and_b32_e32 v97, 0xffff0000, v99
	v_lshlrev_b32_e32 v94, 16, v95
	v_and_b32_e32 v95, 0xffff0000, v95
	v_add_f32_e32 v1, v93, v1
	v_pk_fma_f32 v[94:95], v[96:97], s[4:5], v[94:95] op_sel_hi:[1,0,1]
	v_lshlrev_b32_e32 v96, 16, v116
	v_add_f32_e32 v1, v94, v1
	v_add_f32_e32 v1, v95, v1
	v_add_f32_e32 v1, v88, v1
	v_and_b32_e32 v97, 0xffff0000, v116
	v_lshlrev_b32_e32 v98, 16, v112
	v_and_b32_e32 v99, 0xffff0000, v112
	v_add_f32_e32 v1, v89, v1
	v_pk_fma_f32 v[96:97], v[96:97], s[4:5], v[98:99] op_sel_hi:[1,0,1]
	v_lshlrev_b32_e32 v98, 16, v117
	v_and_b32_e32 v99, 0xffff0000, v117
	v_lshlrev_b32_e32 v100, 16, v113
	v_and_b32_e32 v101, 0xffff0000, v113
	v_add_f32_e32 v1, v90, v1
	v_pk_fma_f32 v[98:99], v[98:99], s[4:5], v[100:101] op_sel_hi:[1,0,1]
	v_lshlrev_b32_e32 v100, 16, v114
	v_and_b32_e32 v101, 0xffff0000, v114
	v_add_f32_e32 v1, v91, v1
	v_pk_fma_f32 v[102:103], v[100:101], s[4:5], v[102:103] op_sel_hi:[1,0,1]
	v_lshlrev_b32_e32 v100, 16, v115
	v_add_f32_e32 v1, v102, v1
	v_and_b32_e32 v101, 0xffff0000, v115
	v_and_b32_e32 v105, 0xffff0000, v111
	v_add_f32_e32 v1, v103, v1
	v_pk_fma_f32 v[104:105], v[100:101], s[4:5], v[104:105] op_sel_hi:[1,0,1]
	v_lshlrev_b32_e32 v100, 16, v82
	v_add_f32_e32 v1, v104, v1
	v_add_f32_e32 v1, v105, v1
	v_add_f32_e32 v1, v96, v1
	v_add_f32_e32 v1, v97, v1
	v_and_b32_e32 v101, 0xffff0000, v82
	v_lshlrev_b32_e32 v110, 16, v78
	v_and_b32_e32 v111, 0xffff0000, v78
	v_lshlrev_b32_e32 v82, 16, v83
	v_and_b32_e32 v83, 0xffff0000, v83
	v_lshlrev_b32_e32 v78, 16, v79
	v_and_b32_e32 v79, 0xffff0000, v79
	v_add_f32_e32 v1, v98, v1
	v_pk_fma_f32 v[100:101], v[100:101], s[4:5], v[110:111] op_sel_hi:[1,0,1]
	v_pk_fma_f32 v[78:79], v[82:83], s[4:5], v[78:79] op_sel_hi:[1,0,1]
	v_lshlrev_b32_e32 v82, 16, v80
	v_and_b32_e32 v83, 0xffff0000, v80
	v_lshlrev_b32_e32 v110, 16, v76
	v_and_b32_e32 v111, 0xffff0000, v76
	v_add_f32_e32 v1, v99, v1
	v_pk_fma_f32 v[82:83], v[82:83], s[4:5], v[110:111] op_sel_hi:[1,0,1]
	v_lshlrev_b32_e32 v80, 16, v81
	v_add_f32_e32 v1, v82, v1
	v_and_b32_e32 v81, 0xffff0000, v81
	v_lshlrev_b32_e32 v76, 16, v77
	v_and_b32_e32 v77, 0xffff0000, v77
	v_add_f32_e32 v1, v83, v1
	v_pk_fma_f32 v[76:77], v[80:81], s[4:5], v[76:77] op_sel_hi:[1,0,1]
	v_lshlrev_b32_e32 v80, 16, v72
	v_add_f32_e32 v1, v76, v1
	v_add_f32_e32 v1, v77, v1
	v_add_f32_e32 v1, v100, v1
	v_add_f32_e32 v1, v101, v1
	v_add_f32_e32 v1, v78, v1
	v_and_b32_e32 v81, 0xffff0000, v72
	v_lshlrev_b32_e32 v110, 16, v68
	v_and_b32_e32 v111, 0xffff0000, v68
	v_add_f32_e32 v1, v79, v1
	v_pk_fma_f32 v[80:81], v[80:81], s[4:5], v[110:111] op_sel_hi:[1,0,1]
	v_lshlrev_b32_e32 v72, 16, v73
	v_add_f32_e32 v1, v80, v1
	v_and_b32_e32 v73, 0xffff0000, v73
	v_lshlrev_b32_e32 v68, 16, v69
	v_and_b32_e32 v69, 0xffff0000, v69
	v_add_f32_e32 v1, v81, v1
	v_pk_fma_f32 v[68:69], v[72:73], s[4:5], v[68:69] op_sel_hi:[1,0,1]
	s_nop 0
	v_add_f32_e32 v1, v68, v1
	v_add_f32_e32 v1, v69, v1
	v_add_f32_e32 v1, v87, v1
	v_add_f32_e32 v1, v86, v1
	v_add_f32_e32 v1, v75, v1
	v_add_f32_e32 v1, v74, v1
	v_mov_b32_e32 v72, v1
	s_nop 1
	v_permlane32_swap_b32 v72, v1
	v_add_f32_e32 v1, v1, v72
	v_mov_b32_e32 v72, v1
	s_nop 1
	v_permlane16_swap_b32 v72, v1
	v_add_f32_e32 v1, v1, v72
	s_nop 1
	v_add_f32_dpp v1, v1, v1 quad_perm:[1,0,3,2] row_mask:0xf bank_mask:0xf
	s_nop 1
	v_add_f32_dpp v1, v1, v1 quad_perm:[2,3,0,1] row_mask:0xf bank_mask:0xf
	s_nop 1
	v_add_f32_dpp v1, v1, v1 row_half_mirror row_mask:0xf bank_mask:0xf
	s_nop 1
	v_add_f32_dpp v1, v1, v1 row_mirror row_mask:0xf bank_mask:0xf
	v_mul_f32_e32 v72, 0x3a000000, v1
	v_pk_add_f32 v[92:93], v[92:93], v[72:73] op_sel_hi:[1,0] neg_lo:[0,1] neg_hi:[0,1]
; __device__ __forceinline__ unsigned cvt_pk_bf16(float lo, float hi) { const f32x2v v = {lo, hi}; const b16x2v r = __builtin_convertvector(v, b16x2v); return __builtin_bit_cast(unsigned, r); }
; __device__ void ln_phase2(const bf16_t* __restrict__ mix, const float* __restrict__ Rf, const bf16_t* __restrict__ Rb, const float* __restrict__ gam, const float* __restrict__ bet, bf16_t* ob, float* of) {
;     ...
;         float q = 0.f;
; #pragma unroll
;         for (int e = 0; e < 32; ++e) { const float dlt = v[e] - mean; q += dlt * dlt; }
; #pragma unroll
;         for (int o = 32; o; o >>= 1) q += __shfl_xor(q, o);
;         const float rstd = rsqrtf(q * (1.0f / 2048.0f) + 1e-5f);
; #pragma unroll
;         for (int j = 0; j < 4; ++j) {
;             const f32x4 g0 = *(const f32x4*)(gam + lane * 8 + 512 * j), g1 = *(const f32x4*)(gam + lane * 8 + 512 * j + 4);
;             const f32x4 b0 = *(const f32x4*)(bet + lane * 8 + 512 * j), b1 = *(const f32x4*)(bet + lane * 8 + 512 * j + 4);
;             f32x4 y0, y1;
; #pragma unroll
;             for (int e = 0; e < 4; ++e) { y0[e] = (v[8 * j + e] - mean) * rstd * g0[e] + b0[e]; y1[e] = (v[8 * j + 4 + e] - mean) * rstd * g1[e] + b1[e]; }
;             if (ob) { u32x4 w; w.x = cvt_pk_bf16(y0[0], y0[1]); w.y = cvt_pk_bf16(y0[2], y0[3]); w.z = cvt_pk_bf16(y1[0], y1[1]); w.w = cvt_pk_bf16(y1[2], y1[3]); *(u32x4*)(ob + ro + 512 * j) = w; }
;             else { *(f32x4*)(of + ro + 512 * j) = y0; *(f32x4*)(of + ro + 512 * j + 4) = y1; }
;         }
;     }
	v_pk_add_f32 v[94:95], v[94:95], v[72:73] op_sel_hi:[1,0] neg_lo:[0,1] neg_hi:[0,1]
	v_pk_mul_f32 v[110:111], v[92:93], v[92:93]
	v_pk_mul_f32 v[112:113], v[94:95], v[94:95]
	v_add_f32_e32 v1, v110, v111
	v_pk_add_f32 v[88:89], v[88:89], v[72:73] op_sel_hi:[1,0] neg_lo:[0,1] neg_hi:[0,1]
	v_add_f32_e32 v1, v112, v1
	v_pk_mul_f32 v[114:115], v[88:89], v[88:89]
	v_add_f32_e32 v1, v113, v1
	v_pk_add_f32 v[90:91], v[90:91], v[72:73] op_sel_hi:[1,0] neg_lo:[0,1] neg_hi:[0,1]
	v_add_f32_e32 v1, v114, v1
	v_pk_mul_f32 v[116:117], v[90:91], v[90:91]
	v_add_f32_e32 v1, v115, v1
	v_pk_add_f32 v[102:103], v[102:103], v[72:73] op_sel_hi:[1,0] neg_lo:[0,1] neg_hi:[0,1]
	v_add_f32_e32 v1, v116, v1
	v_pk_mul_f32 v[118:119], v[102:103], v[102:103]
	v_add_f32_e32 v1, v117, v1
	v_pk_add_f32 v[104:105], v[104:105], v[72:73] op_sel_hi:[1,0] neg_lo:[0,1] neg_hi:[0,1]
	v_add_f32_e32 v1, v118, v1
	v_pk_mul_f32 v[120:121], v[104:105], v[104:105]
	v_add_f32_e32 v1, v119, v1
	v_pk_add_f32 v[96:97], v[96:97], v[72:73] op_sel_hi:[1,0] neg_lo:[0,1] neg_hi:[0,1]
	v_add_f32_e32 v1, v120, v1
	v_pk_mul_f32 v[122:123], v[96:97], v[96:97]
	v_add_f32_e32 v1, v121, v1
	v_pk_add_f32 v[98:99], v[98:99], v[72:73] op_sel_hi:[1,0] neg_lo:[0,1] neg_hi:[0,1]
	v_add_f32_e32 v1, v122, v1
	v_pk_mul_f32 v[124:125], v[98:99], v[98:99]
	v_add_f32_e32 v1, v123, v1
	v_pk_add_f32 v[82:83], v[82:83], v[72:73] op_sel_hi:[1,0] neg_lo:[0,1] neg_hi:[0,1]
	v_add_f32_e32 v1, v124, v1
	v_pk_mul_f32 v[126:127], v[82:83], v[82:83]
	v_add_f32_e32 v1, v125, v1
	v_pk_add_f32 v[128:129], v[76:77], v[72:73] op_sel_hi:[1,0] neg_lo:[0,1] neg_hi:[0,1]
	v_add_f32_e32 v1, v126, v1
	v_pk_mul_f32 v[76:77], v[128:129], v[128:129]
	v_add_f32_e32 v1, v127, v1
	v_pk_add_f32 v[100:101], v[100:101], v[72:73] op_sel_hi:[1,0] neg_lo:[0,1] neg_hi:[0,1]
	v_add_f32_e32 v1, v76, v1
	v_pk_mul_f32 v[130:131], v[100:101], v[100:101]
	v_add_f32_e32 v1, v77, v1
	v_pk_add_f32 v[132:133], v[78:79], v[72:73] op_sel_hi:[1,0] neg_lo:[0,1] neg_hi:[0,1]
	v_add_f32_e32 v1, v130, v1
	v_pk_mul_f32 v[78:79], v[132:133], v[132:133]
	v_add_f32_e32 v1, v131, v1
	v_pk_add_f32 v[80:81], v[80:81], v[72:73] op_sel_hi:[1,0] neg_lo:[0,1] neg_hi:[0,1]
	v_add_f32_e32 v1, v78, v1
	v_pk_mul_f32 v[134:135], v[80:81], v[80:81]
	v_add_f32_e32 v1, v79, v1
	v_pk_add_f32 v[136:137], v[68:69], v[72:73] op_sel_hi:[1,0] neg_lo:[0,1] neg_hi:[0,1]
	v_add_f32_e32 v1, v134, v1
	v_pk_mul_f32 v[68:69], v[136:137], v[136:137]
	v_add_f32_e32 v1, v135, v1
	v_pk_add_f32 v[86:87], v[86:87], v[72:73] op_sel_hi:[1,0] neg_lo:[0,1] neg_hi:[0,1]
	v_add_f32_e32 v1, v68, v1
	v_pk_mul_f32 v[138:139], v[86:87], v[86:87]
	v_add_f32_e32 v1, v69, v1
	v_pk_add_f32 v[140:141], v[74:75], v[72:73] op_sel_hi:[1,0] neg_lo:[0,1] neg_hi:[0,1]
	v_add_f32_e32 v1, v139, v1
	v_pk_mul_f32 v[72:73], v[140:141], v[140:141]
	v_add_f32_e32 v1, v138, v1
	v_add_f32_e32 v1, v73, v1
	v_add_f32_e32 v1, v72, v1
	v_mov_b32_e32 v68, v1
	s_nop 1
	v_permlane32_swap_b32 v68, v1
	v_add_f32_e32 v1, v1, v68
	v_mov_b32_e32 v68, v1
	s_nop 1
	v_permlane16_swap_b32 v68, v1
	v_add_f32_e32 v1, v1, v68
	s_nop 1
	v_add_f32_dpp v1, v1, v1 quad_perm:[1,0,3,2] row_mask:0xf bank_mask:0xf
	s_nop 1
	v_add_f32_dpp v1, v1, v1 quad_perm:[2,3,0,1] row_mask:0xf bank_mask:0xf
	s_nop 1
	v_add_f32_dpp v1, v1, v1 row_half_mirror row_mask:0xf bank_mask:0xf
	s_nop 1
	v_add_f32_dpp v1, v1, v1 row_mirror row_mask:0xf bank_mask:0xf
	v_fmamk_f32 v1, v1, 0x3a000000, v213
	v_cmp_gt_f32_e32 vcc, s12, v1
	v_mul_f32_e32 v68, 0x4b800000, v1
	s_nop 0
	v_cndmask_b32_e32 v1, v1, v68, vcc
	v_rsq_f32_e32 v1, v1
	s_nop 0
	v_mul_f32_e32 v68, 0x45800000, v1
	v_cndmask_b32_e32 v110, v1, v68, vcc
	v_pk_mul_f32 v[68:69], v[92:93], v[110:111] op_sel_hi:[1,0]
	v_pk_mul_f32 v[72:73], v[94:95], v[110:111] op_sel_hi:[1,0]
	v_pk_mul_f32 v[76:77], v[90:91], v[110:111] op_sel_hi:[1,0]
	v_pk_fma_f32 v[74:75], v[10:11], v[72:73], v[18:19]
	v_pk_fma_f32 v[72:73], v[8:9], v[68:69], v[16:17]
	v_pk_mul_f32 v[68:69], v[88:89], v[110:111] op_sel_hi:[1,0]
	v_pk_fma_f32 v[78:79], v[6:7], v[76:77], v[14:15]
	v_pk_fma_f32 v[76:77], v[4:5], v[68:69], v[12:13]
	global_store_dwordx4 v[70:71], v[72:75], off
	global_store_dwordx4 v[70:71], v[76:79], off offset:16
	v_pk_mul_f32 v[68:69], v[102:103], v[110:111] op_sel_hi:[1,0]
	v_pk_mul_f32 v[72:73], v[104:105], v[110:111] op_sel_hi:[1,0]
	v_pk_mul_f32 v[76:77], v[98:99], v[110:111] op_sel_hi:[1,0]
	v_pk_fma_f32 v[74:75], v[26:27], v[72:73], v[34:35]
	v_pk_fma_f32 v[72:73], v[24:25], v[68:69], v[32:33]
	v_pk_mul_f32 v[68:69], v[96:97], v[110:111] op_sel_hi:[1,0]
	v_pk_fma_f32 v[78:79], v[22:23], v[76:77], v[30:31]
	v_pk_fma_f32 v[76:77], v[20:21], v[68:69], v[28:29]
	global_store_dwordx4 v[70:71], v[72:75], off offset:2048
	global_store_dwordx4 v[70:71], v[76:79], off offset:2064
	v_pk_mul_f32 v[68:69], v[82:83], v[110:111] op_sel_hi:[1,0]
	v_pk_mul_f32 v[72:73], v[128:129], v[110:111] op_sel_hi:[1,0]
	v_add_co_u32_e32 v82, vcc, s11, v70
	v_pk_fma_f32 v[74:75], v[38:39], v[72:73], v[46:47]
	v_pk_fma_f32 v[72:73], v[36:37], v[68:69], v[44:45]
	v_pk_mul_f32 v[68:69], v[100:101], v[110:111] op_sel_hi:[1,0]
	v_pk_mul_f32 v[76:77], v[132:133], v[110:111] op_sel_hi:[1,0]
	v_addc_co_u32_e32 v83, vcc, 0, v71, vcc
	v_pk_fma_f32 v[78:79], v[42:43], v[76:77], v[50:51]
	v_pk_fma_f32 v[76:77], v[40:41], v[68:69], v[48:49]
	global_store_dwordx4 v[82:83], v[72:75], off
	global_store_dwordx4 v[82:83], v[76:79], off offset:16
	v_cmp_lt_i32_e32 vcc, s13, v0
	v_pk_mul_f32 v[72:73], v[80:81], v[110:111] op_sel_hi:[1,0]
	v_pk_mul_f32 v[74:75], v[136:137], v[110:111] op_sel_hi:[1,0]
	v_pk_mul_f32 v[68:69], v[86:87], v[110:111] op_sel_hi:[1,0]
	v_pk_mul_f32 v[70:71], v[140:141], v[110:111] op_sel_hi:[1,0]
	v_pk_fma_f32 v[74:75], v[54:55], v[74:75], v[62:63]
	v_pk_fma_f32 v[72:73], v[52:53], v[72:73], v[60:61]
	s_or_b64 s[2:3], vcc, s[2:3]
	v_pk_fma_f32 v[68:69], v[56:57], v[68:69], v[64:65] op_sel:[0,1,0] op_sel_hi:[1,0,1]
	v_pk_fma_f32 v[70:71], v[58:59], v[70:71], v[66:67] op_sel:[0,1,0] op_sel_hi:[1,0,1]
	global_store_dwordx4 v[82:83], v[72:75], off offset:2048
	global_store_dwordx4 v[82:83], v[68:71], off offset:2064
	s_andn2_b64 exec, exec, s[2:3]
	s_cbranch_execnz .LBB0_31

; __device__ __forceinline__ float bflo(unsigned u) { return __uint_as_float(u << 16); }
; __device__ __forceinline__ float bfhi(unsigned u) { return __uint_as_float(u & 0xffff0000u); }
; __device__ void ln_phase2(const bf16_t* __restrict__ mix, const float* __restrict__ Rf, const bf16_t* __restrict__ Rb, const float* __restrict__ gam, const float* __restrict__ bet, bf16_t* ob, float* of) {
;     ...
;     for (int row = blockIdx.x * 8 + wid; row < T_TOK; row += gridDim.x * 8) {
;         const size_t ro = (size_t)row * DM + lane * 8;
;         float v[32]; float s = 0.f;
; #pragma unroll
;         for (int j = 0; j < 4; ++j) {
;             const u32x4 m = *(const u32x4*)(mix + ro + 512 * j);
;             float r[8];
;             if (Rf) { const f32x4 a = *(const f32x4*)(Rf + ro + 512 * j), b = *(const f32x4*)(Rf + ro + 512 * j + 4);
;                 r[0] = a[0]; r[1] = a[1]; r[2] = a[2]; r[3] = a[3]; r[4] = b[0]; r[5] = b[1]; r[6] = b[2]; r[7] = b[3]; }
;             else { const u32x4 rb = *(const u32x4*)(Rb + ro + 512 * j);
;                 r[0] = bflo(rb.x); r[1] = bfhi(rb.x); r[2] = bflo(rb.y); r[3] = bfhi(rb.y); r[4] = bflo(rb.z); r[5] = bfhi(rb.z); r[6] = bflo(rb.w); r[7] = bfhi(rb.w); }
;             v[8 * j + 0] = DN_ALPHA * r[0] + bflo(m.x); v[8 * j + 1] = DN_ALPHA * r[1] + bfhi(m.x); v[8 * j + 2] = DN_ALPHA * r[2] + bflo(m.y); v[8 * j + 3] = DN_ALPHA * r[3] + bfhi(m.y);
;             v[8 * j + 4] = DN_ALPHA * r[4] + bflo(m.z); v[8 * j + 5] = DN_ALPHA * r[5] + bfhi(m.z); v[8 * j + 6] = DN_ALPHA * r[6] + bflo(m.w); v[8 * j + 7] = DN_ALPHA * r[7] + bfhi(m.w);
; #pragma unroll
;             for (int e = 0; e < 8; ++e) s += v[8 * j + e];
;         }
.LBB0_57:
	v_ashrrev_i32_e32 v1, 31, v0
	v_lshlrev_b64 v[78:79], 11, v[0:1]
	v_or_b32_e32 v78, v78, v76
	v_readlane_b32 s0, v254, 11
	v_lshlrev_b64 v[80:81], 1, v[78:79]
	v_readlane_b32 s1, v254, 12
	v_lshl_add_u64 v[84:85], s[64:65], 0, v[80:81]
	v_readlane_b32 s10, v251, 12
	v_lshl_add_u64 v[82:83], s[0:1], 0, v[80:81]
	global_load_dwordx4 v[68:71], v[82:83], off
	global_load_dwordx4 v[72:75], v[84:85], off
	global_load_dwordx4 v[98:101], v[82:83], off offset:1024
	global_load_dwordx4 v[104:107], v[84:85], off offset:1024
	global_load_dwordx4 v[112:115], v[82:83], off offset:2048
	global_load_dwordx4 v[116:119], v[84:85], off offset:2048
	global_load_dwordx4 v[88:91], v[82:83], off offset:3072
	global_load_dwordx4 v[92:95], v[84:85], off offset:3072
	s_mov_b32 s0, 0x3f9837f0
	v_readlane_b32 s11, v251, 13
	v_lshl_add_u64 v[80:81], s[92:93], 0, v[80:81]
	s_waitcnt vmcnt(0)
	v_lshlrev_b32_e32 v96, 16, v114
	v_and_b32_e32 v97, 0xffff0000, v114
	s_waitcnt vmcnt(1)
	v_lshlrev_b32_e32 v84, 16, v91
	s_waitcnt vmcnt(0)
	v_lshlrev_b32_e32 v82, 16, v95
	v_and_b32_e32 v83, 0xffff0000, v95
	v_and_b32_e32 v85, 0xffff0000, v91
	v_pk_fma_f32 v[82:83], v[82:83], s[0:1], v[84:85] op_sel_hi:[1,0,1]
	v_lshlrev_b32_e32 v84, 16, v93
	v_and_b32_e32 v85, 0xffff0000, v93
	v_lshlrev_b32_e32 v86, 16, v89
	v_and_b32_e32 v87, 0xffff0000, v89
	v_pk_fma_f32 v[84:85], v[84:85], s[0:1], v[86:87] op_sel_hi:[1,0,1]
	v_lshlrev_b32_e32 v86, 16, v94
	v_and_b32_e32 v87, 0xffff0000, v94
	v_lshlrev_b32_e32 v94, 16, v90
	v_and_b32_e32 v95, 0xffff0000, v90
	v_lshlrev_b32_e32 v90, 16, v92
	v_and_b32_e32 v91, 0xffff0000, v92
	v_lshlrev_b32_e32 v92, 16, v88
	v_and_b32_e32 v93, 0xffff0000, v88
	v_pk_fma_f32 v[88:89], v[90:91], s[0:1], v[92:93] op_sel_hi:[1,0,1]
	v_lshlrev_b32_e32 v90, 16, v119
	v_and_b32_e32 v91, 0xffff0000, v119
	v_lshlrev_b32_e32 v92, 16, v115
	v_and_b32_e32 v93, 0xffff0000, v115
	v_pk_fma_f32 v[86:87], v[86:87], s[0:1], v[94:95] op_sel_hi:[1,0,1]
	v_pk_fma_f32 v[90:91], v[90:91], s[0:1], v[92:93] op_sel_hi:[1,0,1]
	v_lshlrev_b32_e32 v92, 16, v117
	v_and_b32_e32 v93, 0xffff0000, v117
	v_lshlrev_b32_e32 v94, 16, v113
	v_and_b32_e32 v95, 0xffff0000, v113
	v_pk_fma_f32 v[94:95], v[92:93], s[0:1], v[94:95] op_sel_hi:[1,0,1]
	v_lshlrev_b32_e32 v92, 16, v118
	v_and_b32_e32 v93, 0xffff0000, v118
	v_pk_fma_f32 v[92:93], v[92:93], s[0:1], v[96:97] op_sel_hi:[1,0,1]
	v_lshlrev_b32_e32 v96, 16, v116
	v_and_b32_e32 v97, 0xffff0000, v116
	v_lshlrev_b32_e32 v102, 16, v112
	v_and_b32_e32 v103, 0xffff0000, v112
	v_pk_fma_f32 v[96:97], v[96:97], s[0:1], v[102:103] op_sel_hi:[1,0,1]
	v_lshlrev_b32_e32 v102, 16, v107
	v_and_b32_e32 v103, 0xffff0000, v107
	v_lshlrev_b32_e32 v112, 16, v101
	v_and_b32_e32 v113, 0xffff0000, v101
	v_pk_fma_f32 v[102:103], v[102:103], s[0:1], v[112:113] op_sel_hi:[1,0,1]
	v_lshlrev_b32_e32 v112, 16, v105
	v_and_b32_e32 v113, 0xffff0000, v105
	v_lshlrev_b32_e32 v114, 16, v99
	v_and_b32_e32 v115, 0xffff0000, v99
	v_pk_fma_f32 v[112:113], v[112:113], s[0:1], v[114:115] op_sel_hi:[1,0,1]
	v_lshlrev_b32_e32 v114, 16, v106
	v_and_b32_e32 v115, 0xffff0000, v106
	v_lshlrev_b32_e32 v106, 16, v100
	v_and_b32_e32 v107, 0xffff0000, v100
	v_pk_fma_f32 v[100:101], v[114:115], s[0:1], v[106:107] op_sel_hi:[1,0,1]
	v_lshlrev_b32_e32 v106, 16, v104
	v_and_b32_e32 v107, 0xffff0000, v104
	v_lshlrev_b32_e32 v104, 16, v98
	v_and_b32_e32 v105, 0xffff0000, v98
	v_pk_fma_f32 v[106:107], v[106:107], s[0:1], v[104:105] op_sel_hi:[1,0,1]
	v_lshlrev_b32_e32 v98, 16, v73
	v_and_b32_e32 v99, 0xffff0000, v73
	v_lshlrev_b32_e32 v104, 16, v69
	v_and_b32_e32 v105, 0xffff0000, v69
	v_pk_fma_f32 v[104:105], v[98:99], s[0:1], v[104:105] op_sel_hi:[1,0,1]
	v_lshlrev_b32_e32 v98, 16, v72
	v_and_b32_e32 v99, 0xffff0000, v72
	v_lshlrev_b32_e32 v72, 16, v68
	v_and_b32_e32 v73, 0xffff0000, v68
	v_pk_fma_f32 v[68:69], v[98:99], s[0:1], v[72:73] op_sel_hi:[1,0,1]
	v_lshlrev_b32_e32 v72, 16, v75
	v_add_f32_e32 v1, 0, v68
	v_add_f32_e32 v1, v69, v1
	v_and_b32_e32 v73, 0xffff0000, v75
	v_lshlrev_b32_e32 v98, 16, v71
	v_and_b32_e32 v99, 0xffff0000, v71
	v_add_f32_e32 v1, v104, v1
	v_pk_fma_f32 v[72:73], v[72:73], s[0:1], v[98:99] op_sel_hi:[1,0,1]
	v_lshlrev_b32_e32 v98, 16, v74
	v_and_b32_e32 v99, 0xffff0000, v74
	v_lshlrev_b32_e32 v74, 16, v70
	v_and_b32_e32 v75, 0xffff0000, v70
	v_add_f32_e32 v1, v105, v1
	v_pk_fma_f32 v[70:71], v[98:99], s[0:1], v[74:75] op_sel_hi:[1,0,1]
	s_nop 0
	v_add_f32_e32 v1, v70, v1
	v_add_f32_e32 v1, v71, v1
	v_add_f32_e32 v1, v72, v1
	v_add_f32_e32 v1, v73, v1
	v_add_f32_e32 v1, v106, v1
	v_add_f32_e32 v1, v107, v1
	v_add_f32_e32 v1, v112, v1
	v_add_f32_e32 v1, v113, v1
	v_add_f32_e32 v1, v100, v1
	v_add_f32_e32 v1, v101, v1
	v_add_f32_e32 v1, v102, v1
	v_add_f32_e32 v1, v103, v1
	v_add_f32_e32 v1, v96, v1
	v_add_f32_e32 v1, v97, v1
	v_add_f32_e32 v1, v94, v1
	v_add_f32_e32 v1, v95, v1
	v_add_f32_e32 v1, v92, v1
	v_add_f32_e32 v1, v93, v1
	v_add_f32_e32 v1, v90, v1
	v_add_f32_e32 v1, v91, v1
	v_add_f32_e32 v1, v88, v1
	v_add_f32_e32 v1, v89, v1
	v_add_f32_e32 v1, v84, v1
	v_add_f32_e32 v1, v85, v1
	v_add_f32_e32 v1, v86, v1
	v_add_f32_e32 v1, v87, v1
	v_add_f32_e32 v1, v82, v1
; __device__ __forceinline__ unsigned cvt_pk_bf16(float lo, float hi) { const f32x2v v = {lo, hi}; const b16x2v r = __builtin_convertvector(v, b16x2v); return __builtin_bit_cast(unsigned, r); }
; __device__ void ln_phase2(const bf16_t* __restrict__ mix, const float* __restrict__ Rf, const bf16_t* __restrict__ Rb, const float* __restrict__ gam, const float* __restrict__ bet, bf16_t* ob, float* of) {
;     ...
; #pragma unroll
;         for (int o = 32; o; o >>= 1) s += __shfl_xor(s, o);
;         const float mean = s * (1.0f / 2048.0f);
;         float q = 0.f;
; #pragma unroll
;         for (int e = 0; e < 32; ++e) { const float dlt = v[e] - mean; q += dlt * dlt; }
; #pragma unroll
;         for (int o = 32; o; o >>= 1) q += __shfl_xor(q, o);
;         const float rstd = rsqrtf(q * (1.0f / 2048.0f) + 1e-5f);
; #pragma unroll
;         for (int j = 0; j < 4; ++j) {
;             const f32x4 g0 = *(const f32x4*)(gam + lane * 8 + 512 * j), g1 = *(const f32x4*)(gam + lane * 8 + 512 * j + 4);
;             const f32x4 b0 = *(const f32x4*)(bet + lane * 8 + 512 * j), b1 = *(const f32x4*)(bet + lane * 8 + 512 * j + 4);
;             f32x4 y0, y1;
; #pragma unroll
;             for (int e = 0; e < 4; ++e) { y0[e] = (v[8 * j + e] - mean) * rstd * g0[e] + b0[e]; y1[e] = (v[8 * j + 4 + e] - mean) * rstd * g1[e] + b1[e]; }
;             if (ob) { u32x4 w; w.x = cvt_pk_bf16(y0[0], y0[1]); w.y = cvt_pk_bf16(y0[2], y0[3]); w.z = cvt_pk_bf16(y1[0], y1[1]); w.w = cvt_pk_bf16(y1[2], y1[3]); *(u32x4*)(ob + ro + 512 * j) = w; }
;             else { *(f32x4*)(of + ro + 512 * j) = y0; *(f32x4*)(of + ro + 512 * j + 4) = y1; }
;         }
	v_add_f32_e32 v1, v83, v1
	v_mov_b32_e32 v74, v1
	s_nop 1
	v_permlane32_swap_b32 v74, v1
	v_add_f32_e32 v1, v1, v74
	v_mov_b32_e32 v74, v1
	s_nop 1
	v_permlane16_swap_b32 v74, v1
	v_add_f32_e32 v1, v1, v74
	s_nop 1
	v_add_f32_dpp v1, v1, v1 quad_perm:[1,0,3,2] row_mask:0xf bank_mask:0xf
	s_nop 1
	v_add_f32_dpp v1, v1, v1 quad_perm:[2,3,0,1] row_mask:0xf bank_mask:0xf
	s_nop 1
	v_add_f32_dpp v1, v1, v1 row_half_mirror row_mask:0xf bank_mask:0xf
	s_nop 1
	v_add_f32_dpp v1, v1, v1 row_mirror row_mask:0xf bank_mask:0xf
	v_mul_f32_e32 v114, 0x3a000000, v1
	v_pk_add_f32 v[98:99], v[68:69], v[114:115] op_sel_hi:[1,0] neg_lo:[0,1] neg_hi:[0,1]
	v_pk_add_f32 v[104:105], v[104:105], v[114:115] op_sel_hi:[1,0] neg_lo:[0,1] neg_hi:[0,1]
	v_pk_mul_f32 v[68:69], v[98:99], v[98:99]
	v_pk_mul_f32 v[116:117], v[104:105], v[104:105]
	v_add_f32_e32 v1, v68, v69
	v_pk_add_f32 v[70:71], v[70:71], v[114:115] op_sel_hi:[1,0] neg_lo:[0,1] neg_hi:[0,1]
	v_add_f32_e32 v1, v116, v1
	v_pk_mul_f32 v[118:119], v[70:71], v[70:71]
	v_add_f32_e32 v1, v117, v1
	v_pk_add_f32 v[120:121], v[72:73], v[114:115] op_sel_hi:[1,0] neg_lo:[0,1] neg_hi:[0,1]
	v_add_f32_e32 v1, v118, v1
	v_pk_mul_f32 v[122:123], v[120:121], v[120:121]
	v_add_f32_e32 v1, v119, v1
	v_pk_add_f32 v[72:73], v[106:107], v[114:115] op_sel_hi:[1,0] neg_lo:[0,1] neg_hi:[0,1]
	v_add_f32_e32 v1, v122, v1
	v_pk_mul_f32 v[106:107], v[72:73], v[72:73]
	v_add_f32_e32 v1, v123, v1
	v_pk_add_f32 v[74:75], v[112:113], v[114:115] op_sel_hi:[1,0] neg_lo:[0,1] neg_hi:[0,1]
	v_add_f32_e32 v1, v106, v1
	v_pk_mul_f32 v[112:113], v[74:75], v[74:75]
	v_add_f32_e32 v1, v107, v1
	v_pk_add_f32 v[100:101], v[100:101], v[114:115] op_sel_hi:[1,0] neg_lo:[0,1] neg_hi:[0,1]
	v_add_f32_e32 v1, v112, v1
	v_pk_mul_f32 v[124:125], v[100:101], v[100:101]
	v_add_f32_e32 v1, v113, v1
	v_pk_add_f32 v[102:103], v[102:103], v[114:115] op_sel_hi:[1,0] neg_lo:[0,1] neg_hi:[0,1]
	v_add_f32_e32 v1, v124, v1
	v_pk_mul_f32 v[126:127], v[102:103], v[102:103]
	v_add_f32_e32 v1, v125, v1
	v_pk_add_f32 v[96:97], v[96:97], v[114:115] op_sel_hi:[1,0] neg_lo:[0,1] neg_hi:[0,1]
	v_add_f32_e32 v1, v126, v1
	v_pk_mul_f32 v[128:129], v[96:97], v[96:97]
	v_add_f32_e32 v1, v127, v1
	v_pk_add_f32 v[94:95], v[94:95], v[114:115] op_sel_hi:[1,0] neg_lo:[0,1] neg_hi:[0,1]
	v_add_f32_e32 v1, v128, v1
	v_pk_mul_f32 v[130:131], v[94:95], v[94:95]
	v_add_f32_e32 v1, v129, v1
	v_pk_add_f32 v[92:93], v[92:93], v[114:115] op_sel_hi:[1,0] neg_lo:[0,1] neg_hi:[0,1]
	v_add_f32_e32 v1, v130, v1
	v_pk_mul_f32 v[132:133], v[92:93], v[92:93]
	v_add_f32_e32 v1, v131, v1
	v_pk_add_f32 v[90:91], v[90:91], v[114:115] op_sel_hi:[1,0] neg_lo:[0,1] neg_hi:[0,1]
	v_add_f32_e32 v1, v132, v1
	v_pk_mul_f32 v[134:135], v[90:91], v[90:91]
	v_add_f32_e32 v1, v133, v1
	v_pk_add_f32 v[88:89], v[88:89], v[114:115] op_sel_hi:[1,0] neg_lo:[0,1] neg_hi:[0,1]
	v_add_f32_e32 v1, v134, v1
	v_pk_mul_f32 v[136:137], v[88:89], v[88:89]
	v_add_f32_e32 v1, v135, v1
	v_pk_add_f32 v[84:85], v[84:85], v[114:115] op_sel_hi:[1,0] neg_lo:[0,1] neg_hi:[0,1]
	v_add_f32_e32 v1, v136, v1
	v_pk_mul_f32 v[138:139], v[84:85], v[84:85]
	v_add_f32_e32 v1, v137, v1
	v_pk_add_f32 v[86:87], v[86:87], v[114:115] op_sel_hi:[1,0] neg_lo:[0,1] neg_hi:[0,1]
	v_add_f32_e32 v1, v138, v1
	v_pk_mul_f32 v[140:141], v[86:87], v[86:87]
	v_add_f32_e32 v1, v139, v1
	v_pk_add_f32 v[82:83], v[82:83], v[114:115] op_sel_hi:[1,0] neg_lo:[0,1] neg_hi:[0,1]
	v_add_f32_e32 v1, v140, v1
	v_pk_mul_f32 v[114:115], v[82:83], v[82:83]
	v_add_f32_e32 v1, v141, v1
	v_add_f32_e32 v1, v114, v1
	v_add_f32_e32 v1, v115, v1
	v_mov_b32_e32 v68, v1
	s_nop 1
	v_permlane32_swap_b32 v68, v1
	v_add_f32_e32 v1, v1, v68
	v_mov_b32_e32 v68, v1
	s_nop 1
	v_permlane16_swap_b32 v68, v1
	v_add_f32_e32 v1, v1, v68
	s_nop 1
	v_add_f32_dpp v1, v1, v1 quad_perm:[1,0,3,2] row_mask:0xf bank_mask:0xf
	s_nop 1
	v_add_f32_dpp v1, v1, v1 quad_perm:[2,3,0,1] row_mask:0xf bank_mask:0xf
	s_nop 1
	v_add_f32_dpp v1, v1, v1 row_half_mirror row_mask:0xf bank_mask:0xf
	s_nop 1
	v_add_f32_dpp v1, v1, v1 row_mirror row_mask:0xf bank_mask:0xf
	v_fmamk_f32 v1, v1, 0x3a000000, v213
	v_cmp_gt_f32_e32 vcc, s15, v1
	v_mul_f32_e32 v68, 0x4b800000, v1
	s_nop 0
	v_cndmask_b32_e32 v1, v1, v68, vcc
	v_rsq_f32_e32 v1, v1
	s_nop 0
	v_mul_f32_e32 v68, 0x45800000, v1
	v_cndmask_b32_e32 v106, v1, v68, vcc
	v_mov_b32_e32 v107, v106
	v_pk_mul_f32 v[68:69], v[70:71], v[106:107] op_sel_hi:[1,0]
	v_pk_mul_f32 v[70:71], v[120:121], v[106:107] op_sel_hi:[1,0]
	v_cndmask_b32_e64 v1, 0, 1, s[10:11]
	v_pk_fma_f32 v[68:69], v[4:5], v[68:69], v[8:9]
	v_pk_fma_f32 v[70:71], v[6:7], v[70:71], v[10:11]
	v_cmp_ne_u32_e64 s[0:1], 1, v1
	s_andn2_b64 vcc, exec, s[10:11]
	s_cbranch_vccnz .LBB0_68
	v_pk_mul_f32 v[98:99], v[98:99], v[106:107]
	v_pk_mul_f32 v[104:105], v[104:105], v[106:107]
	v_pk_fma_f32 v[98:99], v[12:13], v[98:99], v[16:17]
	v_pk_fma_f32 v[104:105], v[14:15], v[104:105], v[18:19]
	v_cvt_pk_bf16_f32 v112, v98, v99
	v_cvt_pk_bf16_f32 v113, v104, v105
	v_cvt_pk_bf16_f32 v114, v68, v69
	v_cvt_pk_bf16_f32 v115, v70, v71
	global_store_dwordx4 v[80:81], v[112:115], off
	v_lshlrev_b64 v[78:79], 2, v[78:79]
	s_cbranch_execnz .LBB0_60

; __device__ __forceinline__ float bflo(unsigned u) { return __uint_as_float(u << 16); }
; __device__ __forceinline__ float bfhi(unsigned u) { return __uint_as_float(u & 0xffff0000u); }
; __device__ void ln_phase2(const bf16_t* __restrict__ mix, const float* __restrict__ Rf, const bf16_t* __restrict__ Rb, const float* __restrict__ gam, const float* __restrict__ bet, bf16_t* ob, float* of) {
;     ...
;     for (int row = blockIdx.x * 8 + wid; row < T_TOK; row += gridDim.x * 8) {
;         const size_t ro = (size_t)row * DM + lane * 8;
;         float v[32]; float s = 0.f;
; #pragma unroll
;         for (int j = 0; j < 4; ++j) {
;             const u32x4 m = *(const u32x4*)(mix + ro + 512 * j);
;             float r[8];
;             if (Rf) { const f32x4 a = *(const f32x4*)(Rf + ro + 512 * j), b = *(const f32x4*)(Rf + ro + 512 * j + 4);
;                 r[0] = a[0]; r[1] = a[1]; r[2] = a[2]; r[3] = a[3]; r[4] = b[0]; r[5] = b[1]; r[6] = b[2]; r[7] = b[3]; }
;             else { const u32x4 rb = *(const u32x4*)(Rb + ro + 512 * j);
;                 r[0] = bflo(rb.x); r[1] = bfhi(rb.x); r[2] = bflo(rb.y); r[3] = bfhi(rb.y); r[4] = bflo(rb.z); r[5] = bfhi(rb.z); r[6] = bflo(rb.w); r[7] = bfhi(rb.w); }
;             v[8 * j + 0] = DN_ALPHA * r[0] + bflo(m.x); v[8 * j + 1] = DN_ALPHA * r[1] + bfhi(m.x); v[8 * j + 2] = DN_ALPHA * r[2] + bflo(m.y); v[8 * j + 3] = DN_ALPHA * r[3] + bfhi(m.y);
;             v[8 * j + 4] = DN_ALPHA * r[4] + bflo(m.z); v[8 * j + 5] = DN_ALPHA * r[5] + bfhi(m.z); v[8 * j + 6] = DN_ALPHA * r[6] + bflo(m.w); v[8 * j + 7] = DN_ALPHA * r[7] + bfhi(m.w);
; #pragma unroll
;             for (int e = 0; e < 8; ++e) s += v[8 * j + e];
;         }
; #pragma unroll
;         for (int o = 32; o; o >>= 1) s += __shfl_xor(s, o);
;         const float mean = s * (1.0f / 2048.0f);
;         float q = 0.f;
; #pragma unroll
;         for (int e = 0; e < 32; ++e) { const float dlt = v[e] - mean; q += dlt * dlt; }
.LBB0_93:
	v_ashrrev_i32_e32 v1, 31, v0
	v_lshlrev_b64 v[68:69], 11, v[0:1]
	v_or_b32_e32 v68, v68, v100
	v_lshlrev_b64 v[106:107], 1, v[68:69]
	v_lshl_add_u64 v[68:69], v[68:69], 2, s[72:73]
	v_add_co_u32_e32 v102, vcc, s9, v68
	v_lshl_add_u64 v[70:71], s[26:27], 0, v[106:107]
	v_lshl_add_u64 v[76:77], v[68:69], 0, s[12:13]
	v_addc_co_u32_e32 v103, vcc, 0, v69, vcc
	global_load_dwordx4 v[118:121], v[70:71], off
	global_load_dwordx4 v[122:125], v[68:69], off
	global_load_dwordx4 v[110:113], v[68:69], off offset:16
	global_load_dwordx4 v[88:91], v[70:71], off offset:1024
	global_load_dwordx4 v[92:95], v[68:69], off offset:2048
	global_load_dwordx4 v[96:99], v[68:69], off offset:2064
	global_load_dwordx4 v[72:75], v[70:71], off offset:2048
	global_load_dwordx4 v[80:83], v[102:103], off
	global_load_dwordx4 v[84:87], v[76:77], off offset:16
	s_nop 0
	global_load_dwordx4 v[76:79], v[70:71], off offset:3072
	v_lshl_add_u64 v[104:105], v[68:69], 0, s[16:17]
	global_load_dwordx4 v[68:71], v[102:103], off offset:2048
	s_nop 0
	global_load_dwordx4 v[102:105], v[104:105], off offset:16
	v_add_u32_e32 v0, s8, v0
	s_waitcnt vmcnt(0)
	v_and_b32_e32 v109, 0xffff0000, v78
	v_lshlrev_b32_e32 v108, 16, v78
	v_pk_fma_f32 v[102:103], v[102:103], s[22:23], v[108:109] op_sel_hi:[1,0,1]
	v_and_b32_e32 v109, 0xffff0000, v79
	v_lshlrev_b32_e32 v108, 16, v79
	v_lshl_add_u64 v[78:79], s[64:65], 0, v[106:107]
	v_lshlrev_b32_e32 v106, 16, v121
	v_and_b32_e32 v107, 0xffff0000, v121
	v_pk_fma_f32 v[106:107], v[112:113], s[22:23], v[106:107] op_sel_hi:[1,0,1]
	v_lshlrev_b32_e32 v112, 16, v120
	v_and_b32_e32 v113, 0xffff0000, v120
	v_pk_fma_f32 v[110:111], v[110:111], s[22:23], v[112:113] op_sel_hi:[1,0,1]
	v_lshlrev_b32_e32 v112, 16, v118
	v_and_b32_e32 v113, 0xffff0000, v118
	v_pk_fma_f32 v[112:113], v[122:123], s[22:23], v[112:113] op_sel_hi:[1,0,1]
	v_pk_fma_f32 v[104:105], v[104:105], s[22:23], v[108:109] op_sel_hi:[1,0,1]
	v_lshlrev_b32_e32 v108, 16, v119
	v_and_b32_e32 v109, 0xffff0000, v119
	v_add_f32_e32 v1, 0, v112
	v_pk_fma_f32 v[108:109], v[124:125], s[22:23], v[108:109] op_sel_hi:[1,0,1]
	v_add_f32_e32 v1, v113, v1
	v_add_f32_e32 v1, v108, v1
	v_add_f32_e32 v1, v109, v1
	v_lshlrev_b32_e32 v118, 16, v91
	v_and_b32_e32 v119, 0xffff0000, v91
	v_add_f32_e32 v1, v110, v1
	v_pk_fma_f32 v[98:99], v[98:99], s[22:23], v[118:119] op_sel_hi:[1,0,1]
	v_lshlrev_b32_e32 v118, 16, v89
	v_and_b32_e32 v119, 0xffff0000, v89
	v_add_f32_e32 v1, v111, v1
	v_pk_fma_f32 v[94:95], v[94:95], s[22:23], v[118:119] op_sel_hi:[1,0,1]
	v_lshlrev_b32_e32 v118, 16, v90
	v_and_b32_e32 v119, 0xffff0000, v90
	v_add_f32_e32 v1, v106, v1
	v_pk_fma_f32 v[90:91], v[96:97], s[22:23], v[118:119] op_sel_hi:[1,0,1]
	v_lshlrev_b32_e32 v96, 16, v88
	v_and_b32_e32 v97, 0xffff0000, v88
	v_add_f32_e32 v1, v107, v1
	v_pk_fma_f32 v[88:89], v[92:93], s[22:23], v[96:97] op_sel_hi:[1,0,1]
	v_lshlrev_b32_e32 v92, 16, v75
	v_add_f32_e32 v1, v1, v88
	v_add_f32_e32 v1, v89, v1
	v_add_f32_e32 v1, v94, v1
	v_add_f32_e32 v1, v95, v1
	v_and_b32_e32 v93, 0xffff0000, v75
	v_add_f32_e32 v1, v90, v1
	v_pk_fma_f32 v[86:87], v[86:87], s[22:23], v[92:93] op_sel_hi:[1,0,1]
	v_lshlrev_b32_e32 v92, 16, v73
	v_and_b32_e32 v93, 0xffff0000, v73
	v_add_f32_e32 v1, v91, v1
	v_pk_fma_f32 v[82:83], v[82:83], s[22:23], v[92:93] op_sel_hi:[1,0,1]
	v_lshlrev_b32_e32 v92, 16, v74
	v_and_b32_e32 v93, 0xffff0000, v74
	v_add_f32_e32 v1, v98, v1
	v_pk_fma_f32 v[74:75], v[84:85], s[22:23], v[92:93] op_sel_hi:[1,0,1]
	v_lshlrev_b32_e32 v84, 16, v72
	v_and_b32_e32 v85, 0xffff0000, v72
	v_add_f32_e32 v1, v99, v1
	v_pk_fma_f32 v[72:73], v[80:81], s[22:23], v[84:85] op_sel_hi:[1,0,1]
	v_lshlrev_b32_e32 v80, 16, v77
	v_add_f32_e32 v1, v1, v72
	v_add_f32_e32 v1, v73, v1
	v_add_f32_e32 v1, v82, v1
	v_add_f32_e32 v1, v83, v1
	v_add_f32_e32 v1, v74, v1
	v_add_f32_e32 v1, v75, v1
	v_and_b32_e32 v81, 0xffff0000, v77
	v_add_f32_e32 v1, v86, v1
	v_pk_fma_f32 v[70:71], v[70:71], s[22:23], v[80:81] op_sel_hi:[1,0,1]
	v_lshlrev_b32_e32 v80, 16, v76
	v_and_b32_e32 v81, 0xffff0000, v76
	v_add_f32_e32 v1, v87, v1
	v_pk_fma_f32 v[68:69], v[68:69], s[22:23], v[80:81] op_sel_hi:[1,0,1]
	s_nop 0
	v_add_f32_e32 v1, v1, v68
	v_add_f32_e32 v1, v69, v1
	v_add_f32_e32 v1, v70, v1
	v_add_f32_e32 v1, v71, v1
	v_add_f32_e32 v1, v102, v1
	v_add_f32_e32 v1, v103, v1
	v_add_f32_e32 v1, v104, v1
	v_add_f32_e32 v1, v105, v1
	v_mov_b32_e32 v76, v1
	s_nop 1
	v_permlane32_swap_b32 v76, v1
	v_add_f32_e32 v1, v1, v76
	v_mov_b32_e32 v76, v1
	s_nop 1
	v_permlane16_swap_b32 v76, v1
	v_add_f32_e32 v1, v1, v76
	s_nop 1
	v_add_f32_dpp v1, v1, v1 quad_perm:[1,0,3,2] row_mask:0xf bank_mask:0xf
	s_nop 1
	v_add_f32_dpp v1, v1, v1 quad_perm:[2,3,0,1] row_mask:0xf bank_mask:0xf
	s_nop 1
	v_add_f32_dpp v1, v1, v1 row_half_mirror row_mask:0xf bank_mask:0xf
	s_nop 1
	v_add_f32_dpp v1, v1, v1 row_mirror row_mask:0xf bank_mask:0xf
	v_mul_f32_e32 v92, 0x3a000000, v1
	v_pk_add_f32 v[96:97], v[112:113], v[92:93] op_sel_hi:[1,0] neg_lo:[0,1] neg_hi:[0,1]
	v_pk_add_f32 v[108:109], v[108:109], v[92:93] op_sel_hi:[1,0] neg_lo:[0,1] neg_hi:[0,1]
	v_pk_mul_f32 v[112:113], v[96:97], v[96:97]
	v_pk_mul_f32 v[118:119], v[108:109], v[108:109]
	v_add_f32_e32 v1, v112, v113
	v_pk_add_f32 v[110:111], v[110:111], v[92:93] op_sel_hi:[1,0] neg_lo:[0,1] neg_hi:[0,1]
	v_add_f32_e32 v1, v118, v1
	v_pk_mul_f32 v[120:121], v[110:111], v[110:111]
	v_add_f32_e32 v1, v119, v1
	v_pk_add_f32 v[106:107], v[106:107], v[92:93] op_sel_hi:[1,0] neg_lo:[0,1] neg_hi:[0,1]
	v_add_f32_e32 v1, v120, v1
	v_pk_mul_f32 v[122:123], v[106:107], v[106:107]
	v_add_f32_e32 v1, v121, v1
	v_pk_add_f32 v[124:125], v[88:89], v[92:93] op_sel_hi:[1,0] neg_lo:[0,1] neg_hi:[0,1]
; __device__ __forceinline__ unsigned cvt_pk_bf16(float lo, float hi) { const f32x2v v = {lo, hi}; const b16x2v r = __builtin_convertvector(v, b16x2v); return __builtin_bit_cast(unsigned, r); }
; __device__ void ln_phase2(const bf16_t* __restrict__ mix, const float* __restrict__ Rf, const bf16_t* __restrict__ Rb, const float* __restrict__ gam, const float* __restrict__ bet, bf16_t* ob, float* of) {
;     ...
;         float q = 0.f;
; #pragma unroll
;         for (int e = 0; e < 32; ++e) { const float dlt = v[e] - mean; q += dlt * dlt; }
; #pragma unroll
;         for (int o = 32; o; o >>= 1) q += __shfl_xor(q, o);
;         const float rstd = rsqrtf(q * (1.0f / 2048.0f) + 1e-5f);
; #pragma unroll
;         for (int j = 0; j < 4; ++j) {
;             const f32x4 g0 = *(const f32x4*)(gam + lane * 8 + 512 * j), g1 = *(const f32x4*)(gam + lane * 8 + 512 * j + 4);
;             const f32x4 b0 = *(const f32x4*)(bet + lane * 8 + 512 * j), b1 = *(const f32x4*)(bet + lane * 8 + 512 * j + 4);
;             f32x4 y0, y1;
; #pragma unroll
;             for (int e = 0; e < 4; ++e) { y0[e] = (v[8 * j + e] - mean) * rstd * g0[e] + b0[e]; y1[e] = (v[8 * j + 4 + e] - mean) * rstd * g1[e] + b1[e]; }
;             if (ob) { u32x4 w; w.x = cvt_pk_bf16(y0[0], y0[1]); w.y = cvt_pk_bf16(y0[2], y0[3]); w.z = cvt_pk_bf16(y1[0], y1[1]); w.w = cvt_pk_bf16(y1[2], y1[3]); *(u32x4*)(ob + ro + 512 * j) = w; }
;             else { *(f32x4*)(of + ro + 512 * j) = y0; *(f32x4*)(of + ro + 512 * j + 4) = y1; }
;         }
	v_add_f32_e32 v1, v122, v1
	v_pk_mul_f32 v[88:89], v[124:125], v[124:125]
	v_add_f32_e32 v1, v123, v1
	v_pk_add_f32 v[94:95], v[94:95], v[92:93] op_sel_hi:[1,0] neg_lo:[0,1] neg_hi:[0,1]
	v_add_f32_e32 v1, v88, v1
	v_pk_mul_f32 v[126:127], v[94:95], v[94:95]
	v_add_f32_e32 v1, v89, v1
	v_pk_add_f32 v[90:91], v[90:91], v[92:93] op_sel_hi:[1,0] neg_lo:[0,1] neg_hi:[0,1]
	v_add_f32_e32 v1, v126, v1
	v_pk_mul_f32 v[128:129], v[90:91], v[90:91]
	v_add_f32_e32 v1, v127, v1
	v_pk_add_f32 v[98:99], v[98:99], v[92:93] op_sel_hi:[1,0] neg_lo:[0,1] neg_hi:[0,1]
	v_add_f32_e32 v1, v128, v1
	v_pk_mul_f32 v[130:131], v[98:99], v[98:99]
	v_add_f32_e32 v1, v129, v1
	v_pk_add_f32 v[80:81], v[72:73], v[92:93] op_sel_hi:[1,0] neg_lo:[0,1] neg_hi:[0,1]
	v_add_f32_e32 v1, v130, v1
	v_pk_mul_f32 v[132:133], v[80:81], v[80:81]
	v_add_f32_e32 v1, v131, v1
	v_pk_add_f32 v[76:77], v[82:83], v[92:93] op_sel_hi:[1,0] neg_lo:[0,1] neg_hi:[0,1]
	v_add_f32_e32 v1, v132, v1
	v_pk_mul_f32 v[134:135], v[76:77], v[76:77]
	v_add_f32_e32 v1, v133, v1
	v_pk_add_f32 v[84:85], v[74:75], v[92:93] op_sel_hi:[1,0] neg_lo:[0,1] neg_hi:[0,1]
	v_add_f32_e32 v1, v134, v1
	v_pk_mul_f32 v[136:137], v[84:85], v[84:85]
	v_add_f32_e32 v1, v135, v1
	v_pk_add_f32 v[82:83], v[86:87], v[92:93] op_sel_hi:[1,0] neg_lo:[0,1] neg_hi:[0,1]
	v_add_f32_e32 v1, v136, v1
	v_pk_mul_f32 v[86:87], v[82:83], v[82:83]
	v_add_f32_e32 v1, v137, v1
	v_pk_add_f32 v[68:69], v[68:69], v[92:93] op_sel_hi:[1,0] neg_lo:[0,1] neg_hi:[0,1]
	v_add_f32_e32 v1, v86, v1
	v_pk_mul_f32 v[138:139], v[68:69], v[68:69]
	v_add_f32_e32 v1, v87, v1
	v_pk_add_f32 v[70:71], v[70:71], v[92:93] op_sel_hi:[1,0] neg_lo:[0,1] neg_hi:[0,1]
	v_add_f32_e32 v1, v138, v1
	v_pk_mul_f32 v[140:141], v[70:71], v[70:71]
	v_add_f32_e32 v1, v139, v1
	v_pk_add_f32 v[74:75], v[102:103], v[92:93] op_sel_hi:[1,0] neg_lo:[0,1] neg_hi:[0,1]
	v_add_f32_e32 v1, v140, v1
	v_pk_add_f32 v[72:73], v[104:105], v[92:93] op_sel_hi:[1,0] neg_lo:[0,1] neg_hi:[0,1]
	v_pk_mul_f32 v[92:93], v[74:75], v[74:75]
	v_add_f32_e32 v1, v141, v1
	v_add_f32_e32 v1, v92, v1
	v_pk_mul_f32 v[104:105], v[72:73], v[72:73]
	v_add_f32_e32 v1, v93, v1
	v_add_f32_e32 v1, v104, v1
	v_add_f32_e32 v1, v105, v1
	v_mov_b32_e32 v86, v1
	s_nop 1
	v_permlane32_swap_b32 v86, v1
	v_add_f32_e32 v1, v1, v86
	v_mov_b32_e32 v86, v1
	s_nop 1
	v_permlane16_swap_b32 v86, v1
	v_add_f32_e32 v1, v1, v86
	s_nop 1
	v_add_f32_dpp v1, v1, v1 quad_perm:[1,0,3,2] row_mask:0xf bank_mask:0xf
	s_nop 1
	v_add_f32_dpp v1, v1, v1 quad_perm:[2,3,0,1] row_mask:0xf bank_mask:0xf
	s_nop 1
	v_add_f32_dpp v1, v1, v1 row_half_mirror row_mask:0xf bank_mask:0xf
	s_nop 1
	v_add_f32_dpp v1, v1, v1 row_mirror row_mask:0xf bank_mask:0xf
	v_fmamk_f32 v1, v1, 0x3a000000, v213
	v_cmp_gt_f32_e32 vcc, s15, v1
	v_mul_f32_e32 v86, 0x4b800000, v1
	s_nop 0
	v_cndmask_b32_e32 v1, v1, v86, vcc
	v_rsq_f32_e32 v1, v1
	s_nop 0
	v_mul_f32_e32 v86, 0x45800000, v1
	v_cndmask_b32_e32 v92, v1, v86, vcc
	v_pk_mul_f32 v[86:87], v[96:97], v[92:93] op_sel_hi:[1,0]
	v_pk_mul_f32 v[88:89], v[110:111], v[92:93] op_sel_hi:[1,0]
	v_pk_mul_f32 v[96:97], v[108:109], v[92:93] op_sel_hi:[1,0]
	v_pk_mul_f32 v[102:103], v[106:107], v[92:93] op_sel_hi:[1,0]
	v_pk_fma_f32 v[86:87], v[4:5], v[86:87], v[8:9]
	v_pk_fma_f32 v[88:89], v[12:13], v[88:89], v[16:17]
	v_pk_fma_f32 v[96:97], v[6:7], v[96:97], v[10:11]
	v_pk_fma_f32 v[102:103], v[14:15], v[102:103], v[18:19]
	v_cvt_pk_bf16_f32 v86, v86, v87
	v_cvt_pk_bf16_f32 v87, v96, v97
	v_cvt_pk_bf16_f32 v88, v88, v89
	v_cvt_pk_bf16_f32 v89, v102, v103
	global_store_dwordx4 v[78:79], v[86:89], off
	v_pk_mul_f32 v[80:81], v[80:81], v[92:93] op_sel_hi:[1,0]
	v_pk_mul_f32 v[84:85], v[84:85], v[92:93] op_sel_hi:[1,0]
	v_pk_mul_f32 v[86:87], v[124:125], v[92:93] op_sel_hi:[1,0]
	v_pk_mul_f32 v[88:89], v[90:91], v[92:93] op_sel_hi:[1,0]
	v_pk_mul_f32 v[90:91], v[94:95], v[92:93] op_sel_hi:[1,0]
	v_pk_mul_f32 v[94:95], v[98:99], v[92:93] op_sel_hi:[1,0]
	v_pk_fma_f32 v[86:87], v[20:21], v[86:87], v[24:25]
	v_pk_fma_f32 v[88:89], v[28:29], v[88:89], v[32:33]
	v_pk_fma_f32 v[90:91], v[22:23], v[90:91], v[26:27]
	v_pk_fma_f32 v[94:95], v[30:31], v[94:95], v[34:35]
	v_cvt_pk_bf16_f32 v86, v86, v87
	v_cvt_pk_bf16_f32 v87, v90, v91
	v_cvt_pk_bf16_f32 v88, v88, v89
	v_cvt_pk_bf16_f32 v89, v94, v95
	v_pk_mul_f32 v[76:77], v[76:77], v[92:93] op_sel_hi:[1,0]
	v_pk_mul_f32 v[82:83], v[82:83], v[92:93] op_sel_hi:[1,0]
	v_pk_mul_f32 v[68:69], v[68:69], v[92:93] op_sel_hi:[1,0]
	v_pk_mul_f32 v[74:75], v[74:75], v[92:93] op_sel_hi:[1,0]
	v_pk_mul_f32 v[70:71], v[70:71], v[92:93] op_sel_hi:[1,0]
	v_pk_mul_f32 v[72:73], v[72:73], v[92:93] op_sel_hi:[1,0]
	global_store_dwordx4 v[78:79], v[86:89], off offset:1024
	v_pk_fma_f32 v[80:81], v[36:37], v[80:81], v[44:45]
	v_pk_fma_f32 v[84:85], v[40:41], v[84:85], v[48:49]
	v_pk_fma_f32 v[76:77], v[38:39], v[76:77], v[46:47]
	v_pk_fma_f32 v[86:87], v[42:43], v[82:83], v[50:51]
	v_pk_fma_f32 v[68:69], v[52:53], v[68:69], v[60:61]
	v_pk_fma_f32 v[74:75], v[56:57], v[74:75], v[64:65]
	v_pk_fma_f32 v[70:71], v[54:55], v[70:71], v[62:63]
	v_pk_fma_f32 v[72:73], v[58:59], v[72:73], v[66:67]
	v_cmp_lt_i32_e32 vcc, s18, v0
	v_cvt_pk_bf16_f32 v80, v80, v81
	v_cvt_pk_bf16_f32 v81, v76, v77
	v_cvt_pk_bf16_f32 v82, v84, v85
	v_cvt_pk_bf16_f32 v83, v86, v87
	v_cvt_pk_bf16_f32 v68, v68, v69
	v_cvt_pk_bf16_f32 v69, v70, v71
	v_cvt_pk_bf16_f32 v70, v74, v75
	v_cvt_pk_bf16_f32 v71, v72, v73
	s_or_b64 s[2:3], vcc, s[2:3]
	global_store_dwordx4 v[78:79], v[80:83], off offset:2048
	global_store_dwordx4 v[78:79], v[68:71], off offset:3072
	s_andn2_b64 exec, exec, s[2:3]
	s_cbranch_execnz .LBB0_93

; __device__ __forceinline__ float bflo(unsigned u) { return __uint_as_float(u << 16); }
; __device__ __forceinline__ float bfhi(unsigned u) { return __uint_as_float(u & 0xffff0000u); }
; __device__ __forceinline__ float silu_f(float v) { return v / (1.0f + fexp2(-v * LOG2E)); }
; __device__ void merge_phase(const Params& p) {
;     ...
;         { const int hh = lane >> 4, sub = lane & 15;
;           const bf16_t* src = og + (size_t)tok * 1024 + hh * 256 + sub * 16;
;           const u32x4 a = *(const u32x4*)src, b = *(const u32x4*)(src + 8);
;           float xv[16];
; #pragma unroll
;           for (int j = 0; j < 4; ++j) { xv[2 * j] = bflo(a[j]); xv[2 * j + 1] = bfhi(a[j]); xv[8 + 2 * j] = bflo(b[j]); xv[8 + 2 * j + 1] = bfhi(b[j]); }
;           float s = 0.f;
; #pragma unroll
;           for (int j = 0; j < 16; ++j) s += xv[j];
;           s += __shfl_xor(s, 1); s += __shfl_xor(s, 2); s += __shfl_xor(s, 4); s += __shfl_xor(s, 8);
;           const float mean = s * (1.0f / 256.0f);
;           float q = 0.f;
; #pragma unroll
;           for (int j = 0; j < 16; ++j) { const float dlt = xv[j] - mean; q += dlt * dlt; }
;           q += __shfl_xor(q, 1); q += __shfl_xor(q, 2); q += __shfl_xor(q, 4); q += __shfl_xor(q, 8);
;           const float rstd = rsqrtf(q * (1.0f / 256.0f) + 1e-5f);
;           const bf16_t* rgp = h + (size_t)tok * HC + 2048 + hh * 256 + sub * 16;
;           const u32x4 ra = *(const u32x4*)rgp, rb = *(const u32x4*)(rgp + 8);
;           const float* ngp = p.norm_g + hh * 256 + sub * 16;
;           float ov[16];
; #pragma unroll
;           for (int j4 = 0; j4 < 4; ++j4) { const f32x4 ng = *(const f32x4*)(ngp + 4 * j4);
; #pragma unroll
;               for (int j = 0; j < 4; ++j) { const int e = 4 * j4 + j; const unsigned rw = (e < 8) ? ra[e >> 1] : rb[(e - 8) >> 1]; const float rv = (e & 1) ? bfhi(rw) : bflo(rw);
;                   ov[e] = (xv[e] - mean) * rstd * ng[j] * silu_f(rv); } }
.LBB0_100:
	v_ashrrev_i32_e32 v1, 31, v0
	v_lshlrev_b64 v[50:51], 11, v[0:1]
	v_lshl_add_u64 v[4:5], v[36:37], 0, v[50:51]
	global_load_dwordx4 v[24:27], v[4:5], off
	global_load_dwordx4 v[32:35], v[4:5], off offset:16
	v_mov_b64_e32 v[4:5], s[92:93]
	v_mad_i64_i32 v[52:53], s[6:7], v0, s48, v[4:5]
	v_lshl_add_u64 v[4:5], v[52:53], 0, v[2:3]
	v_mov_b32_e32 v41, v3
	v_lshl_add_u64 v[4:5], v[4:5], 0, v[40:41]
	s_mov_b64 s[6:7], 0xd101000
	v_lshl_add_u64 v[6:7], v[4:5], 0, s[6:7]
	s_mov_b32 s6, 0xd101000
	v_add_co_u32_e32 v4, vcc, s6, v4
	s_waitcnt vmcnt(0)
	v_lshlrev_b32_e32 v58, 16, v27
	v_addc_co_u32_e32 v5, vcc, 0, v5, vcc
	global_load_dwordx4 v[28:31], v[4:5], off
	s_nop 0
	global_load_dwordx4 v[4:7], v[6:7], off offset:16
	s_nop 0
	global_load_dwordx4 v[8:11], v[38:39], off offset:48
	global_load_dwordx4 v[12:15], v[38:39], off offset:32
	global_load_dwordx4 v[20:23], v[38:39], off
	global_load_dwordx4 v[16:19], v[38:39], off offset:16
	v_and_b32_e32 v59, 0xffff0000, v27
	v_lshlrev_b32_e32 v56, 16, v35
	v_and_b32_e32 v57, 0xffff0000, v35
	v_and_b32_e32 v61, 0xffff0000, v34
	v_and_b32_e32 v63, 0xffff0000, v26
	v_and_b32_e32 v65, 0xffff0000, v33
	v_lshlrev_b32_e32 v68, 16, v25
	v_and_b32_e32 v69, 0xffff0000, v25
	v_lshlrev_b32_e32 v70, 16, v32
	v_and_b32_e32 v71, 0xffff0000, v32
	s_waitcnt vmcnt(0)
	v_lshlrev_b32_e32 v27, 16, v31
	v_and_b32_e32 v31, 0xffff0000, v31
	v_mul_f32_e32 v35, 0xbfb8aa3b, v27
	v_exp_f32_e32 v54, v35
	v_mul_f32_e32 v35, 0xbfb8aa3b, v31
	v_exp_f32_e32 v55, v35
	s_nop 0
	v_pk_add_f32 v[54:55], v[54:55], 1.0 op_sel_hi:[1,0]
	s_nop 0
	v_div_scale_f32 v35, s[6:7], v55, v55, v31
	v_rcp_f32_e32 v43, v35
	s_nop 0
	v_fma_f32 v47, -v35, v43, 1.0
	v_fmac_f32_e32 v43, v47, v43
	v_div_scale_f32 v47, vcc, v31, v55, v31
	v_mul_f32_e32 v49, v47, v43
	v_fma_f32 v60, -v35, v49, v47
	v_fmac_f32_e32 v49, v60, v43
	v_fma_f32 v35, -v35, v49, v47
	v_div_fmas_f32 v35, v35, v43, v49
	v_div_fixup_f32 v55, v35, v55, v31
	v_div_scale_f32 v31, s[6:7], v54, v54, v27
	v_rcp_f32_e32 v35, v31
	v_lshlrev_b32_e32 v60, 16, v34
	v_fma_f32 v43, -v31, v35, 1.0
	v_fmac_f32_e32 v35, v43, v35
	v_div_scale_f32 v43, vcc, v27, v54, v27
	v_mul_f32_e32 v47, v43, v35
	v_fma_f32 v49, -v31, v47, v43
	v_fmac_f32_e32 v47, v49, v35
	v_fma_f32 v31, -v31, v47, v43
	v_div_fmas_f32 v31, v31, v35, v47
	v_div_fixup_f32 v54, v31, v54, v27
	v_lshlrev_b32_e32 v27, 16, v6
	v_and_b32_e32 v6, 0xffff0000, v6
	v_mul_f32_e32 v31, 0xbfb8aa3b, v27
	v_exp_f32_e32 v34, v31
	v_mul_f32_e32 v31, 0xbfb8aa3b, v6
	v_exp_f32_e32 v35, v31
	s_nop 0
	v_pk_add_f32 v[34:35], v[34:35], 1.0 op_sel_hi:[1,0]
	s_nop 0
	v_div_scale_f32 v31, s[6:7], v35, v35, v6
	v_rcp_f32_e32 v43, v31
	s_nop 0
	v_fma_f32 v47, -v31, v43, 1.0
	v_fmac_f32_e32 v43, v47, v43
	v_div_scale_f32 v47, vcc, v6, v35, v6
	v_mul_f32_e32 v49, v47, v43
	v_fma_f32 v62, -v31, v49, v47
	v_fmac_f32_e32 v49, v62, v43
	v_fma_f32 v31, -v31, v49, v47
	v_div_fmas_f32 v31, v31, v43, v49
	v_div_fixup_f32 v35, v31, v35, v6
	v_div_scale_f32 v6, s[6:7], v34, v34, v27
	v_rcp_f32_e32 v31, v6
	v_lshlrev_b32_e32 v62, 16, v26
	v_fma_f32 v43, -v6, v31, 1.0
	v_fmac_f32_e32 v31, v43, v31
	v_div_scale_f32 v43, vcc, v27, v34, v27
	v_mul_f32_e32 v47, v43, v31
	v_fma_f32 v49, -v6, v47, v43
	v_fmac_f32_e32 v47, v49, v31
	v_fma_f32 v6, -v6, v47, v43
	v_div_fmas_f32 v6, v6, v31, v47
	v_div_fixup_f32 v34, v6, v34, v27
	v_lshlrev_b32_e32 v6, 16, v30
	v_and_b32_e32 v30, 0xffff0000, v30
	v_mul_f32_e32 v26, 0xbfb8aa3b, v6
	v_mul_f32_e32 v27, 0xbfb8aa3b, v30
	v_exp_f32_e32 v26, v26
	v_exp_f32_e32 v27, v27
	s_nop 0
	v_pk_add_f32 v[26:27], v[26:27], 1.0 op_sel_hi:[1,0]
	s_nop 0
	v_div_scale_f32 v31, s[6:7], v27, v27, v30
	v_rcp_f32_e32 v43, v31
	s_nop 0
	v_fma_f32 v47, -v31, v43, 1.0
	v_fmac_f32_e32 v43, v47, v43
	v_div_scale_f32 v47, vcc, v30, v27, v30
	v_mul_f32_e32 v49, v47, v43
	v_fma_f32 v64, -v31, v49, v47
	v_fmac_f32_e32 v49, v64, v43
	v_fma_f32 v31, -v31, v49, v47
	v_div_fmas_f32 v31, v31, v43, v49
	v_div_fixup_f32 v27, v31, v27, v30
	v_div_scale_f32 v30, s[6:7], v26, v26, v6
	v_rcp_f32_e32 v31, v30
	v_lshlrev_b32_e32 v64, 16, v33
	v_fma_f32 v43, -v30, v31, 1.0
	v_fmac_f32_e32 v31, v43, v31
	v_div_scale_f32 v43, vcc, v6, v26, v6
	v_mul_f32_e32 v47, v43, v31
	v_fma_f32 v49, -v30, v47, v43
	v_fmac_f32_e32 v47, v49, v31
	v_fma_f32 v30, -v30, v47, v43
	v_div_fmas_f32 v30, v30, v31, v47
	v_div_fixup_f32 v26, v30, v26, v6
	v_lshlrev_b32_e32 v6, 16, v5
	v_and_b32_e32 v5, 0xffff0000, v5
	v_mul_f32_e32 v30, 0xbfb8aa3b, v6
	v_mul_f32_e32 v31, 0xbfb8aa3b, v5
	v_exp_f32_e32 v30, v30
	v_exp_f32_e32 v31, v31
	s_nop 0
	v_pk_add_f32 v[30:31], v[30:31], 1.0 op_sel_hi:[1,0]
	s_nop 0
	v_div_scale_f32 v33, s[6:7], v31, v31, v5
	v_rcp_f32_e32 v43, v33
	s_nop 0
	v_fma_f32 v47, -v33, v43, 1.0
	v_fmac_f32_e32 v43, v47, v43
	v_div_scale_f32 v47, vcc, v5, v31, v5
	v_mul_f32_e32 v49, v47, v43
	v_fma_f32 v66, -v33, v49, v47
	v_fmac_f32_e32 v49, v66, v43
	v_fma_f32 v33, -v33, v49, v47
	v_div_fmas_f32 v33, v33, v43, v49
	v_div_fixup_f32 v31, v33, v31, v5
	v_div_scale_f32 v5, s[6:7], v30, v30, v6
	v_rcp_f32_e32 v33, v5
	s_nop 0
	v_fma_f32 v43, -v5, v33, 1.0
	v_fmac_f32_e32 v33, v43, v33
	v_div_scale_f32 v43, vcc, v6, v30, v6
	v_mul_f32_e32 v47, v43, v33
	v_fma_f32 v49, -v5, v47, v43
	v_fmac_f32_e32 v47, v49, v33
	v_fma_f32 v5, -v5, v47, v43
	v_div_fmas_f32 v5, v5, v33, v47
	v_div_fixup_f32 v30, v5, v30, v6
	v_lshlrev_b32_e32 v5, 16, v29
	v_and_b32_e32 v6, 0xffff0000, v29
	v_mul_f32_e32 v25, 0xbfb8aa3b, v5
	v_exp_f32_e32 v66, v25
	v_mul_f32_e32 v25, 0xbfb8aa3b, v6
	v_exp_f32_e32 v67, v25
	s_nop 0
	v_pk_add_f32 v[66:67], v[66:67], 1.0 op_sel_hi:[1,0]
	s_nop 0
	v_div_scale_f32 v25, s[6:7], v67, v67, v6
; __device__ __forceinline__ float bflo(unsigned u) { return __uint_as_float(u << 16); }
; __device__ __forceinline__ float bfhi(unsigned u) { return __uint_as_float(u & 0xffff0000u); }
; __device__ __forceinline__ float silu_f(float v) { return v / (1.0f + fexp2(-v * LOG2E)); }
; __device__ void merge_phase(const Params& p) {
;     ...
;           float s = 0.f;
; #pragma unroll
;           for (int j = 0; j < 16; ++j) s += xv[j];
;           s += __shfl_xor(s, 1); s += __shfl_xor(s, 2); s += __shfl_xor(s, 4); s += __shfl_xor(s, 8);
;           const float mean = s * (1.0f / 256.0f);
;           float q = 0.f;
; #pragma unroll
;           for (int j = 0; j < 16; ++j) { const float dlt = xv[j] - mean; q += dlt * dlt; }
;           q += __shfl_xor(q, 1); q += __shfl_xor(q, 2); q += __shfl_xor(q, 4); q += __shfl_xor(q, 8);
;           const float rstd = rsqrtf(q * (1.0f / 256.0f) + 1e-5f);
;           const bf16_t* rgp = h + (size_t)tok * HC + 2048 + hh * 256 + sub * 16;
;           const u32x4 ra = *(const u32x4*)rgp, rb = *(const u32x4*)(rgp + 8);
;           const float* ngp = p.norm_g + hh * 256 + sub * 16;
;           float ov[16];
; #pragma unroll
;           for (int j4 = 0; j4 < 4; ++j4) { const f32x4 ng = *(const f32x4*)(ngp + 4 * j4);
; #pragma unroll
;               for (int j = 0; j < 4; ++j) { const int e = 4 * j4 + j; const unsigned rw = (e < 8) ? ra[e >> 1] : rb[(e - 8) >> 1]; const float rv = (e & 1) ? bfhi(rw) : bflo(rw);
;                   ov[e] = (xv[e] - mean) * rstd * ng[j] * silu_f(rv); } }
	v_rcp_f32_e32 v29, v25
	s_nop 0
	v_fma_f32 v33, -v25, v29, 1.0
	v_fmac_f32_e32 v29, v33, v29
	v_div_scale_f32 v33, vcc, v6, v67, v6
	v_mul_f32_e32 v43, v33, v29
	v_fma_f32 v47, -v25, v43, v33
	v_fmac_f32_e32 v43, v47, v29
	v_fma_f32 v25, -v25, v43, v33
	v_div_fmas_f32 v25, v25, v29, v43
	v_div_fixup_f32 v67, v25, v67, v6
	v_div_scale_f32 v6, s[6:7], v66, v66, v5
	v_rcp_f32_e32 v25, v6
	s_nop 0
	v_fma_f32 v29, -v6, v25, 1.0
	v_fmac_f32_e32 v25, v29, v25
	v_div_scale_f32 v29, vcc, v5, v66, v5
	v_mul_f32_e32 v33, v29, v25
	v_fma_f32 v43, -v6, v33, v29
	v_fmac_f32_e32 v33, v43, v25
	v_fma_f32 v6, -v6, v33, v29
	v_div_fmas_f32 v6, v6, v25, v33
	v_div_fixup_f32 v66, v6, v66, v5
	v_lshlrev_b32_e32 v6, 16, v4
	v_and_b32_e32 v25, 0xffff0000, v4
	v_mul_f32_e32 v4, 0xbfb8aa3b, v6
	v_mul_f32_e32 v5, 0xbfb8aa3b, v25
	v_exp_f32_e32 v4, v4
	v_exp_f32_e32 v5, v5
	s_nop 0
	v_pk_add_f32 v[4:5], v[4:5], 1.0 op_sel_hi:[1,0]
	s_nop 0
	v_div_scale_f32 v29, s[6:7], v5, v5, v25
	v_rcp_f32_e32 v32, v29
	s_nop 0
	v_fma_f32 v33, -v29, v32, 1.0
	v_fmac_f32_e32 v32, v33, v32
	v_div_scale_f32 v33, vcc, v25, v5, v25
	v_mul_f32_e32 v43, v33, v32
	v_fma_f32 v47, -v29, v43, v33
	v_fmac_f32_e32 v43, v47, v32
	v_fma_f32 v29, -v29, v43, v33
	v_div_fmas_f32 v29, v29, v32, v43
	v_div_fixup_f32 v5, v29, v5, v25
	v_div_scale_f32 v25, s[6:7], v4, v4, v6
	v_rcp_f32_e32 v29, v25
	s_nop 0
	v_fma_f32 v32, -v25, v29, 1.0
	v_fmac_f32_e32 v29, v32, v29
	v_div_scale_f32 v32, vcc, v6, v4, v6
	v_mul_f32_e32 v33, v32, v29
	v_fma_f32 v43, -v25, v33, v32
	v_fmac_f32_e32 v33, v43, v29
	v_fma_f32 v25, -v25, v33, v32
	v_div_fmas_f32 v25, v25, v29, v33
	v_lshlrev_b32_e32 v29, 16, v28
	v_and_b32_e32 v28, 0xffff0000, v28
	v_div_fixup_f32 v4, v25, v4, v6
	v_lshlrev_b32_e32 v32, 16, v24
	v_and_b32_e32 v33, 0xffff0000, v24
	v_mul_f32_e32 v24, 0xbfb8aa3b, v29
	v_mul_f32_e32 v25, 0xbfb8aa3b, v28
	v_exp_f32_e32 v24, v24
	v_exp_f32_e32 v25, v25
	v_add_f32_e32 v6, 0, v32
	v_add_f32_e32 v6, v6, v33
	v_add_f32_e32 v6, v6, v68
	v_pk_add_f32 v[24:25], v[24:25], 1.0 op_sel_hi:[1,0]
	v_add_f32_e32 v6, v6, v69
	v_div_scale_f32 v43, s[6:7], v25, v25, v28
	v_rcp_f32_e32 v47, v43
	v_add_f32_e32 v6, v6, v62
	v_add_f32_e32 v6, v6, v63
	v_add_f32_e32 v6, v6, v58
	v_fma_f32 v49, -v43, v47, 1.0
	v_fmac_f32_e32 v47, v49, v47
	v_div_scale_f32 v49, vcc, v28, v25, v28
	v_mul_f32_e32 v76, v49, v47
	v_fma_f32 v77, -v43, v76, v49
	v_fmac_f32_e32 v76, v77, v47
	v_fma_f32 v43, -v43, v76, v49
	v_div_fmas_f32 v43, v43, v47, v76
	v_div_fixup_f32 v25, v43, v25, v28
	v_div_scale_f32 v28, s[6:7], v24, v24, v29
	v_rcp_f32_e32 v43, v28
	v_add_f32_e32 v6, v6, v59
	v_add_f32_e32 v6, v6, v70
	v_add_f32_e32 v6, v6, v71
	v_fma_f32 v47, -v28, v43, 1.0
	v_fmac_f32_e32 v43, v47, v43
	v_div_scale_f32 v47, vcc, v29, v24, v29
	v_add_f32_e32 v6, v6, v64
	v_mul_f32_e32 v49, v47, v43
	v_add_f32_e32 v6, v6, v65
	v_fma_f32 v76, -v28, v49, v47
	v_add_f32_e32 v6, v6, v60
	v_fmac_f32_e32 v49, v76, v43
	v_add_f32_e32 v6, v6, v61
	v_fma_f32 v28, -v28, v49, v47
	v_add_f32_e32 v6, v6, v56
	v_div_fmas_f32 v28, v28, v43, v49
	v_add_f32_e32 v6, v6, v57
	v_div_fixup_f32 v24, v28, v24, v29
	v_mov_b32_e32 v43, v3
	v_mov_b32_e32 v47, v3
	v_mov_b32_e32 v49, v3
	s_nop 1
	v_add_f32_dpp v6, v6, v6 quad_perm:[1,0,3,2] row_mask:0xf bank_mask:0xf
	s_nop 1
	v_add_f32_dpp v6, v6, v6 quad_perm:[2,3,0,1] row_mask:0xf bank_mask:0xf
	s_nop 1
	v_add_f32_dpp v6, v6, v6 row_half_mirror row_mask:0xf bank_mask:0xf
	s_nop 1
	v_add_f32_dpp v6, v6, v6 row_mirror row_mask:0xf bank_mask:0xf
	v_mul_f32_e32 v6, 0x3b800000, v6
	v_pk_add_f32 v[28:29], v[32:33], v[6:7] op_sel_hi:[1,0] neg_lo:[0,1] neg_hi:[0,1]
	v_pk_add_f32 v[68:69], v[68:69], v[6:7] op_sel_hi:[1,0] neg_lo:[0,1] neg_hi:[0,1]
	v_pk_mul_f32 v[32:33], v[28:29], v[28:29]
	v_pk_mul_f32 v[76:77], v[68:69], v[68:69]
	v_pk_add_f32 v[62:63], v[62:63], v[6:7] op_sel_hi:[1,0] neg_lo:[0,1] neg_hi:[0,1]
	v_pk_add_f32 v[58:59], v[58:59], v[6:7] op_sel_hi:[1,0] neg_lo:[0,1] neg_hi:[0,1]
	v_pk_add_f32 v[70:71], v[70:71], v[6:7] op_sel_hi:[1,0] neg_lo:[0,1] neg_hi:[0,1]
	v_pk_add_f32 v[64:65], v[64:65], v[6:7] op_sel_hi:[1,0] neg_lo:[0,1] neg_hi:[0,1]
	v_pk_add_f32 v[60:61], v[60:61], v[6:7] op_sel_hi:[1,0] neg_lo:[0,1] neg_hi:[0,1]
	v_pk_add_f32 v[56:57], v[56:57], v[6:7] op_sel_hi:[1,0] neg_lo:[0,1] neg_hi:[0,1]
	v_add_f32_e32 v6, v32, v33
	v_add_f32_e32 v6, v76, v6
	v_pk_mul_f32 v[78:79], v[62:63], v[62:63]
	v_add_f32_e32 v6, v77, v6
	v_add_f32_e32 v6, v78, v6
	v_pk_mul_f32 v[80:81], v[58:59], v[58:59]
	v_add_f32_e32 v6, v79, v6
	v_add_f32_e32 v6, v80, v6
	v_pk_mul_f32 v[82:83], v[70:71], v[70:71]
	v_add_f32_e32 v6, v81, v6
	v_add_f32_e32 v6, v82, v6
	v_pk_mul_f32 v[84:85], v[64:65], v[64:65]
	v_add_f32_e32 v6, v83, v6
	v_add_f32_e32 v6, v84, v6
	v_pk_mul_f32 v[86:87], v[60:61], v[60:61]
	v_add_f32_e32 v6, v85, v6
	v_add_f32_e32 v6, v86, v6
	v_pk_mul_f32 v[88:89], v[56:57], v[56:57]
	v_add_f32_e32 v6, v87, v6
	v_add_f32_e32 v6, v88, v6
	v_add_f32_e32 v6, v89, v6
	s_nop 1
	v_add_f32_dpp v6, v6, v6 quad_perm:[1,0,3,2] row_mask:0xf bank_mask:0xf
	s_nop 1
	v_add_f32_dpp v6, v6, v6 quad_perm:[2,3,0,1] row_mask:0xf bank_mask:0xf
	s_nop 1
	v_add_f32_dpp v6, v6, v6 row_half_mirror row_mask:0xf bank_mask:0xf
	s_nop 1
	v_add_f32_dpp v6, v6, v6 row_mirror row_mask:0xf bank_mask:0xf
	v_fmamk_f32 v6, v6, 0x3b800000, v213
	v_cmp_gt_f32_e32 vcc, s15, v6
	v_mul_f32_e32 v32, 0x4b800000, v6
	s_nop 0
	v_cndmask_b32_e32 v6, v6, v32, vcc
	v_rsq_f32_e32 v6, v6
	s_nop 0
	v_mul_f32_e32 v32, 0x45800000, v6
	v_cndmask_b32_e32 v6, v6, v32, vcc
	v_pk_mul_f32 v[28:29], v[28:29], v[6:7] op_sel_hi:[1,0]
	s_nop 0
	v_pk_mul_f32 v[20:21], v[20:21], v[28:29]
	s_nop 0
; __device__ __forceinline__ unsigned cvt_pk_bf16(float lo, float hi) { const f32x2v v = {lo, hi}; const b16x2v r = __builtin_convertvector(v, b16x2v); return __builtin_bit_cast(unsigned, r); }
; __device__ __forceinline__ float bflo(unsigned u) { return __uint_as_float(u << 16); }
; __device__ __forceinline__ float bfhi(unsigned u) { return __uint_as_float(u & 0xffff0000u); }
; __device__ __forceinline__ float fexp2(float x) { return __builtin_amdgcn_exp2f(x); }
; __device__ __forceinline__ float silu_f(float v) { return v / (1.0f + fexp2(-v * LOG2E)); }
; __device__ void merge_phase(const Params& p) {
;     ...
;           for (int j4 = 0; j4 < 4; ++j4) { const f32x4 ng = *(const f32x4*)(ngp + 4 * j4);
; #pragma unroll
;               for (int j = 0; j < 4; ++j) { const int e = 4 * j4 + j; const unsigned rw = (e < 8) ? ra[e >> 1] : rb[(e - 8) >> 1]; const float rv = (e & 1) ? bfhi(rw) : bflo(rw);
;                   ov[e] = (xv[e] - mean) * rstd * ng[j] * silu_f(rv); } }
;           u32x4 o0, o1;
; #pragma unroll
;           for (int j = 0; j < 4; ++j) { o0[j] = cvt_pk_bf16(ov[2 * j], ov[2 * j + 1]); o1[j] = cvt_pk_bf16(ov[8 + 2 * j], ov[8 + 2 * j + 1]); }
;           bf16_t* dst = mix + (size_t)tok * DM + hh * 256 + sub * 16;
;           *(u32x4*)dst = o0; *(u32x4*)(dst + 8) = o1; }
;         { const int hd = lane >> 3, sub = lane & 7;
;           const float l0 = lse[(size_t)tok * 8 + hd], l1 = lse[(size_t)T_TOK * 8 + (size_t)tok * 8 + hd], l2 = lse[(size_t)2 * T_TOK * 8 + (size_t)tok * 8 + hd];
;           const float m = fmaxf(l0, fmaxf(l1, l2));
;           float e0 = fexp2((l0 - m) * LOG2E), e1 = fexp2((l1 - m) * LOG2E), e2 = fexp2((l2 - m) * LOG2E);
;           const float inv = 1.0f / (e0 + e1 + e2); e0 *= inv; e1 *= inv; e2 *= inv;
;           const size_t so = (size_t)tok * 1024 + hd * 128 + sub * 16;
;           u32x4 o[2];
; #pragma unroll
;           for (int hf = 0; hf < 2; ++hf) { const u32x4 a = *(const u32x4*)(od0 + so + 8 * hf), b = *(const u32x4*)(od1 + so + 8 * hf), c = *(const u32x4*)(od2 + so + 8 * hf);
; #pragma unroll
;               for (int j = 0; j < 4; ++j) o[hf][j] = cvt_pk_bf16(e0 * bflo(a[j]) + e1 * bflo(b[j]) + e2 * bflo(c[j]), e0 * bfhi(a[j]) + e1 * bfhi(b[j]) + e2 * bfhi(c[j])); }
	v_pk_mul_f32 v[20:21], v[24:25], v[20:21]
	v_pk_mul_f32 v[24:25], v[68:69], v[6:7] op_sel_hi:[1,0]
	s_nop 0
	v_pk_mul_f32 v[22:23], v[22:23], v[24:25]
	v_pk_mul_f32 v[24:25], v[62:63], v[6:7] op_sel_hi:[1,0]
	v_pk_mul_f32 v[22:23], v[66:67], v[22:23]
	v_pk_mul_f32 v[16:17], v[16:17], v[24:25]
	v_pk_mul_f32 v[24:25], v[58:59], v[6:7] op_sel_hi:[1,0]
	v_pk_mul_f32 v[16:17], v[26:27], v[16:17]
	v_pk_mul_f32 v[18:19], v[18:19], v[24:25]
	v_pk_mul_f32 v[24:25], v[70:71], v[6:7] op_sel_hi:[1,0]
	v_pk_mul_f32 v[18:19], v[54:55], v[18:19]
	v_pk_mul_f32 v[12:13], v[12:13], v[24:25]
	s_nop 0
	v_pk_mul_f32 v[12:13], v[4:5], v[12:13]
	v_pk_mul_f32 v[4:5], v[64:65], v[6:7] op_sel_hi:[1,0]
	s_nop 0
	v_pk_mul_f32 v[4:5], v[14:15], v[4:5]
	s_nop 0
	v_pk_mul_f32 v[14:15], v[30:31], v[4:5]
	v_pk_mul_f32 v[4:5], v[60:61], v[6:7] op_sel_hi:[1,0]
	s_nop 0
	v_pk_mul_f32 v[4:5], v[8:9], v[4:5]
	v_lshlrev_b32_e32 v8, 16, v7
	v_and_b32_e32 v9, 0xffff0000, v7
	v_pk_mul_f32 v[24:25], v[34:35], v[4:5]
	v_mul_f32_e32 v4, 0xbfb8aa3b, v8
	v_mul_f32_e32 v5, 0xbfb8aa3b, v9
	v_exp_f32_e32 v4, v4
	v_exp_f32_e32 v5, v5
	v_pk_mul_f32 v[6:7], v[56:57], v[6:7] op_sel_hi:[1,0]
	v_pk_add_f32 v[4:5], v[4:5], 1.0 op_sel_hi:[1,0]
	v_pk_mul_f32 v[6:7], v[10:11], v[6:7]
	v_div_scale_f32 v10, s[6:7], v5, v5, v9
	v_rcp_f32_e32 v11, v10
	s_nop 0
	v_fma_f32 v26, -v10, v11, 1.0
	v_fmac_f32_e32 v11, v26, v11
	v_div_scale_f32 v26, vcc, v9, v5, v9
	v_mul_f32_e32 v27, v26, v11
	v_fma_f32 v28, -v10, v27, v26
	v_fmac_f32_e32 v27, v28, v11
	v_fma_f32 v10, -v10, v27, v26
	v_div_fmas_f32 v10, v10, v11, v27
	v_div_fixup_f32 v5, v10, v5, v9
	v_div_scale_f32 v9, s[6:7], v4, v4, v8
	v_rcp_f32_e32 v10, v9
	s_mov_b32 s6, 0x100000
	v_fma_f32 v11, -v9, v10, 1.0
	v_fmac_f32_e32 v10, v11, v10
	v_div_scale_f32 v11, vcc, v8, v4, v8
	v_mul_f32_e32 v26, v11, v10
	v_fma_f32 v27, -v9, v26, v11
	v_fmac_f32_e32 v26, v27, v10
	v_fma_f32 v9, -v9, v26, v11
	v_div_fmas_f32 v9, v9, v10, v26
	v_div_fixup_f32 v4, v9, v4, v8
	v_cvt_pk_bf16_f32 v8, v12, v13
	v_lshlrev_b64 v[12:13], 13, v[0:1]
	v_sub_co_u32_e32 v12, vcc, 0, v12
	v_pk_mul_f32 v[26:27], v[4:5], v[6:7]
	s_nop 0
	v_subb_co_u32_e32 v13, vcc, 0, v13, vcc
	v_cvt_pk_bf16_f32 v6, v16, v17
	v_lshl_add_u64 v[16:17], v[52:53], 0, v[12:13]
	v_lshl_add_u64 v[12:13], v[16:17], 0, v[2:3]
	v_cvt_pk_bf16_f32 v4, v20, v21
	v_cvt_pk_bf16_f32 v5, v22, v23
	v_cvt_pk_bf16_f32 v7, v18, v19
	v_lshl_add_u64 v[12:13], v[12:13], 0, v[40:41]
	v_cvt_pk_bf16_f32 v9, v14, v15
	v_cvt_pk_bf16_f32 v10, v24, v25
	v_cvt_pk_bf16_f32 v11, v26, v27
	global_store_dwordx4 v[12:13], v[4:7], off
	global_store_dwordx4 v[12:13], v[8:11], off offset:16
	s_nop 0
	v_lshlrev_b64 v[4:5], 5, v[0:1]
	v_lshl_add_u64 v[4:5], s[12:13], 0, v[4:5]
	v_lshl_add_u64 v[4:5], v[4:5], 0, v[42:43]
	v_add_co_u32_e32 v6, vcc, s9, v4
	global_load_dword v1, v[4:5], off
	s_nop 0
	v_addc_co_u32_e32 v7, vcc, 0, v5, vcc
	global_load_dword v6, v[6:7], off
	v_add_co_u32_e32 v4, vcc, s6, v4
	v_add_u32_e32 v0, s8, v0
	s_nop 0
	v_addc_co_u32_e32 v5, vcc, 0, v5, vcc
	global_load_dword v4, v[4:5], off
	s_waitcnt vmcnt(0)
	v_max3_f32 v5, v1, v6, v4
	v_sub_f32_e32 v1, v1, v5
	v_mul_f32_e32 v1, 0x3fb8aa3b, v1
	v_exp_f32_e32 v21, v1
	v_sub_f32_e32 v1, v6, v5
	v_mul_f32_e32 v1, 0x3fb8aa3b, v1
	v_exp_f32_e32 v20, v1
	v_sub_f32_e32 v1, v4, v5
	v_mul_f32_e32 v1, 0x3fb8aa3b, v1
	v_exp_f32_e32 v1, v1
	v_add_f32_e32 v4, v21, v20
	v_add_f32_e32 v4, v1, v4
	v_div_scale_f32 v5, s[6:7], v4, v4, 1.0
	v_rcp_f32_e32 v6, v5
	s_nop 0
	v_fma_f32 v7, -v5, v6, 1.0
	v_fmac_f32_e32 v6, v7, v6
	v_div_scale_f32 v7, vcc, 1.0, v4, 1.0
	v_mul_f32_e32 v8, v7, v6
	v_fma_f32 v9, -v5, v8, v7
	v_fmac_f32_e32 v8, v9, v6
	v_fma_f32 v5, -v5, v8, v7
	v_div_fmas_f32 v5, v5, v6, v8
	v_div_fixup_f32 v22, v5, v4, 1.0
	v_or_b32_e32 v5, v51, v45
	v_or_b32_e32 v4, v50, v44
	v_lshl_add_u64 v[8:9], s[54:55], 0, v[4:5]
	v_lshl_add_u64 v[12:13], s[10:11], 0, v[4:5]
	v_lshl_add_u64 v[32:33], s[24:25], 0, v[4:5]
	global_load_dwordx4 v[4:7], v[8:9], off offset:16
	global_load_dwordx4 v[24:27], v[8:9], off
	s_nop 0
	global_load_dwordx4 v[8:11], v[12:13], off offset:16
	global_load_dwordx4 v[28:31], v[12:13], off
	s_nop 0
	global_load_dwordx4 v[12:15], v[32:33], off offset:16
	s_nop 0
	global_load_dwordx4 v[32:35], v[32:33], off
	v_mul_f32_e32 v18, v1, v22
	v_pk_mul_f32 v[50:51], v[20:21], v[22:23] op_sel_hi:[1,0]
	v_cmp_lt_i32_e32 vcc, s18, v0
	s_or_b64 s[2:3], vcc, s[2:3]
	s_waitcnt vmcnt(4)
; __device__ __forceinline__ unsigned cvt_pk_bf16(float lo, float hi) { const f32x2v v = {lo, hi}; const b16x2v r = __builtin_convertvector(v, b16x2v); return __builtin_bit_cast(unsigned, r); }
; __device__ __forceinline__ float bflo(unsigned u) { return __uint_as_float(u << 16); }
; __device__ __forceinline__ float bfhi(unsigned u) { return __uint_as_float(u & 0xffff0000u); }
; __device__ void merge_phase(const Params& p) {
;     ...
;           for (int hf = 0; hf < 2; ++hf) { const u32x4 a = *(const u32x4*)(od0 + so + 8 * hf), b = *(const u32x4*)(od1 + so + 8 * hf), c = *(const u32x4*)(od2 + so + 8 * hf);
; #pragma unroll
;               for (int j = 0; j < 4; ++j) o[hf][j] = cvt_pk_bf16(e0 * bflo(a[j]) + e1 * bflo(b[j]) + e2 * bflo(c[j]), e0 * bfhi(a[j]) + e1 * bfhi(b[j]) + e2 * bfhi(c[j])); }
;           bf16_t* dst = mix + (size_t)tok * DM + 1024 + hd * 128 + sub * 16;
;           *(u32x4*)dst = o[0]; *(u32x4*)(dst + 8) = o[1]; }
	v_lshlrev_b32_e32 v22, 16, v24
	v_and_b32_e32 v21, 0xffff0000, v24
	s_waitcnt vmcnt(2)
	v_and_b32_e32 v23, 0xffff0000, v28
	v_lshlrev_b32_e32 v20, 16, v28
	v_pk_mul_f32 v[22:23], v[50:51], v[22:23] op_sel:[1,0] op_sel_hi:[0,1]
	v_pk_fma_f32 v[20:21], v[50:51], v[20:21], v[22:23]
	v_and_b32_e32 v23, 0xffff0000, v25
	v_lshlrev_b32_e32 v24, 16, v25
	v_and_b32_e32 v25, 0xffff0000, v29
	v_lshlrev_b32_e32 v22, 16, v29
	v_pk_mul_f32 v[24:25], v[50:51], v[24:25] op_sel:[1,0] op_sel_hi:[0,1]
	s_waitcnt vmcnt(0)
	v_lshlrev_b32_e32 v52, 16, v32
	v_and_b32_e32 v53, 0xffff0000, v32
	v_lshlrev_b32_e32 v28, 16, v33
	v_and_b32_e32 v29, 0xffff0000, v33
	v_pk_fma_f32 v[22:23], v[50:51], v[22:23], v[24:25]
	v_pk_fma_f32 v[20:21], v[18:19], v[52:53], v[20:21] op_sel_hi:[0,1,1]
	v_pk_fma_f32 v[22:23], v[18:19], v[28:29], v[22:23] op_sel_hi:[0,1,1]
	v_lshlrev_b32_e32 v24, 16, v26
	v_and_b32_e32 v25, 0xffff0000, v30
	v_cvt_pk_bf16_f32 v20, v20, v21
	v_cvt_pk_bf16_f32 v21, v22, v23
	v_lshlrev_b32_e32 v22, 16, v30
	v_and_b32_e32 v23, 0xffff0000, v26
	v_pk_mul_f32 v[24:25], v[50:51], v[24:25] op_sel:[1,0] op_sel_hi:[0,1]
	v_pk_fma_f32 v[22:23], v[50:51], v[22:23], v[24:25]
	v_and_b32_e32 v25, 0xffff0000, v27
	v_lshlrev_b32_e32 v26, 16, v27
	v_and_b32_e32 v27, 0xffff0000, v31
	v_lshlrev_b32_e32 v28, 16, v34
	v_and_b32_e32 v29, 0xffff0000, v34
	v_lshlrev_b32_e32 v24, 16, v31
	v_pk_mul_f32 v[26:27], v[50:51], v[26:27] op_sel:[1,0] op_sel_hi:[0,1]
	v_pk_fma_f32 v[22:23], v[18:19], v[28:29], v[22:23] op_sel_hi:[0,1,1]
	v_lshlrev_b32_e32 v28, 16, v35
	v_and_b32_e32 v29, 0xffff0000, v35
	v_pk_fma_f32 v[24:25], v[50:51], v[24:25], v[26:27]
	v_lshlrev_b32_e32 v26, 16, v4
	v_pk_fma_f32 v[24:25], v[18:19], v[28:29], v[24:25] op_sel_hi:[0,1,1]
	v_and_b32_e32 v27, 0xffff0000, v8
	v_cvt_pk_bf16_f32 v22, v22, v23
	v_cvt_pk_bf16_f32 v23, v24, v25
	v_lshlrev_b32_e32 v24, 16, v8
	v_and_b32_e32 v25, 0xffff0000, v4
	v_pk_mul_f32 v[26:27], v[50:51], v[26:27] op_sel:[1,0] op_sel_hi:[0,1]
	v_lshlrev_b32_e32 v28, 16, v12
	v_and_b32_e32 v29, 0xffff0000, v12
	v_pk_fma_f32 v[24:25], v[50:51], v[24:25], v[26:27]
	v_lshlrev_b32_e32 v8, 16, v5
	v_pk_fma_f32 v[24:25], v[18:19], v[28:29], v[24:25] op_sel_hi:[0,1,1]
	v_cvt_pk_bf16_f32 v4, v24, v25
	v_lshlrev_b32_e32 v24, 16, v9
	v_and_b32_e32 v9, 0xffff0000, v9
	v_and_b32_e32 v25, 0xffff0000, v5
	v_pk_mul_f32 v[8:9], v[50:51], v[8:9] op_sel:[1,0] op_sel_hi:[0,1]
	v_lshlrev_b32_e32 v12, 16, v13
	v_and_b32_e32 v13, 0xffff0000, v13
	v_pk_fma_f32 v[8:9], v[50:51], v[24:25], v[8:9]
	v_lshlrev_b32_e32 v24, 16, v14
	v_pk_fma_f32 v[8:9], v[18:19], v[12:13], v[8:9] op_sel_hi:[0,1,1]
	v_lshlrev_b32_e32 v12, 16, v6
	v_and_b32_e32 v13, 0xffff0000, v10
	v_cvt_pk_bf16_f32 v5, v8, v9
	v_lshlrev_b32_e32 v8, 16, v10
	v_and_b32_e32 v9, 0xffff0000, v6
	v_pk_mul_f32 v[12:13], v[50:51], v[12:13] op_sel:[1,0] op_sel_hi:[0,1]
	v_and_b32_e32 v25, 0xffff0000, v14
	v_pk_fma_f32 v[8:9], v[50:51], v[8:9], v[12:13]
	v_lshlrev_b32_e32 v10, 16, v7
	v_pk_fma_f32 v[8:9], v[18:19], v[24:25], v[8:9] op_sel_hi:[0,1,1]
	v_cvt_pk_bf16_f32 v6, v8, v9
	v_lshlrev_b32_e32 v8, 16, v11
	v_and_b32_e32 v11, 0xffff0000, v11
	v_and_b32_e32 v9, 0xffff0000, v7
	v_pk_mul_f32 v[10:11], v[50:51], v[10:11] op_sel:[1,0] op_sel_hi:[0,1]
	v_pk_fma_f32 v[8:9], v[50:51], v[8:9], v[10:11]
	v_lshlrev_b32_e32 v10, 16, v15
	v_and_b32_e32 v11, 0xffff0000, v15
	v_pk_fma_f32 v[8:9], v[18:19], v[10:11], v[8:9] op_sel_hi:[0,1,1]
	v_cvt_pk_bf16_f32 v7, v8, v9
	v_lshl_add_u64 v[8:9], v[16:17], 0, v[46:47]
	v_lshl_add_u64 v[8:9], v[8:9], 0, v[48:49]
	global_store_dwordx4 v[8:9], v[20:23], off offset:2048
	global_store_dwordx4 v[8:9], v[4:7], off offset:2064
	s_andn2_b64 exec, exec, s[2:3]
	s_cbranch_execnz .LBB0_100
